# merge phase (P3) output stores made non-temporal (streamed once, next read from other XCDs)
# speedup vs baseline: 1.0016x; 1.0014x over previous
.LBB0_471:
	v_ashrrev_i32_e32 v7, 31, v5
	v_and_b32_e32 v8, 0xffffff00, v5
	v_add_u32_sdwa v7, v5, v7 dst_sel:DWORD dst_unused:UNUSED_PAD src0_sel:DWORD src1_sel:BYTE_3
	v_add_u32_e32 v5, s1, v5
	v_ashrrev_i32_e32 v7, 8, v7
	v_cmp_lt_i32_e32 vcc, s13, v5
	v_mul_i32_i24_e32 v9, 0x100, v7
	v_add_u32_e32 v7, 0x4000, v7
	s_or_b64 s[10:11], vcc, s[10:11]
	v_cmp_ne_u32_e32 vcc, s12, v8
	s_nop 1
	v_cndmask_b32_e32 v8, -1, v7, vcc
	v_lshlrev_b32_e32 v7, 3, v9
	v_ashrrev_i32_e32 v9, 31, v8
	v_sub_u32_e32 v10, v6, v7
	v_lshlrev_b64 v[8:9], 12, v[8:9]
	v_ashrrev_i32_e32 v11, 31, v10
	v_lshl_add_u64 v[8:9], s[8:9], 0, v[8:9]
	v_add_u32_e32 v6, s3, v6
	v_lshl_add_u64 v[8:9], v[10:11], 1, v[8:9]
	global_store_dwordx4 v[8:9], v[0:3], off nt
	s_andn2_b64 exec, exec, s[10:11]
	s_cbranch_execnz .LBB0_471

.LBB0_474:
	s_ashr_i32 s11, s10, 31
	v_lshl_add_u64 v[120:121], s[10:11], 1, v[66:67]
	v_lshl_add_u64 v[0:1], v[120:121], 0, v[34:35]
	global_load_dwordx4 v[0:3], v[0:1], off nt
	v_lshl_add_u64 v[108:109], v[120:121], 0, v[58:59]
	v_lshl_add_u64 v[112:113], v[120:121], 0, v[60:61]
	v_lshl_add_u64 v[4:5], v[120:121], 0, v[36:37]
	global_load_dwordx4 v[108:111], v[108:109], off nt
	v_lshl_add_u64 v[116:117], v[120:121], 0, v[62:63]
	global_load_dwordx4 v[112:115], v[112:113], off nt
	v_lshl_add_u64 v[8:9], v[120:121], 0, v[38:39]
	global_load_dwordx4 v[4:7], v[4:5], off nt
	v_lshl_add_u64 v[12:13], v[120:121], 0, v[40:41]
	global_load_dwordx4 v[116:119], v[116:117], off nt
	v_lshl_add_u64 v[16:17], v[120:121], 0, v[42:43]
	global_load_dwordx4 v[8:11], v[8:9], off nt
	v_lshl_add_u64 v[20:21], v[120:121], 0, v[44:45]
	v_lshl_add_u64 v[24:25], v[120:121], 0, v[46:47]
	v_lshl_add_u64 v[28:29], v[120:121], 0, v[48:49]
	v_lshl_add_u64 v[70:71], v[120:121], 0, v[50:51]
	v_lshl_add_u64 v[74:75], v[120:121], 0, v[52:53]
	v_lshl_add_u64 v[78:79], v[120:121], 0, v[54:55]
	v_lshl_add_u64 v[104:105], v[120:121], 0, v[56:57]
	v_lshl_add_u64 v[120:121], v[120:121], 0, v[64:65]
	global_load_dwordx4 v[120:123], v[120:121], off nt
	v_add_u32_e32 v124, v82, v83
	global_load_dwordx4 v[12:15], v[12:13], off nt
	v_add_u32_e32 v125, 0x2100, v32
	global_load_dwordx4 v[16:19], v[16:17], off nt
	v_add_u32_e32 v126, 0x2108, v32
	global_load_dwordx4 v[20:23], v[20:21], off nt
	v_add_u32_e32 v127, 0x4200, v32
	global_load_dwordx4 v[24:27], v[24:25], off nt
	v_add_u32_e32 v128, 0x4208, v32
	global_load_dwordx4 v[28:31], v[28:29], off nt
	v_add_u32_e32 v129, 0x6300, v32
	global_load_dwordx4 v[70:73], v[70:71], off nt
	v_add_u32_e32 v130, 0x6308, v32
	global_load_dwordx4 v[74:77], v[74:75], off nt
	v_add_u32_e32 v131, 0x8400, v32
	global_load_dwordx4 v[78:81], v[78:79], off nt
	v_add_u32_e32 v132, 0x8408, v32
	global_load_dwordx4 v[104:107], v[104:105], off nt
	v_add_u32_e32 v133, 0xa500, v32
	v_add_u32_e32 v134, 0xa508, v32
	v_add_u32_e32 v135, 0xc600, v32
	v_add_u32_e32 v136, 0xc608, v32
	v_add_u32_e32 v137, 0xe700, v32
	v_add_u32_e32 v138, 0xe708, v32
	v_add_u32_e32 v139, 0x2100, v124
	v_add_u32_e32 v140, 0x2108, v124
	v_add_u32_e32 v141, 0x4200, v124
	v_add_u32_e32 v142, 0x4208, v124
	v_add_u32_e32 v143, 0x6300, v124
	v_add_u32_e32 v144, 0x6308, v124
	v_add_u32_e32 v145, 0x8400, v124
	v_add_u32_e32 v146, 0x8408, v124
	v_add_u32_e32 v147, 0xa500, v124
	s_lshl_b64 s[0:1], s[10:11], 3
	s_add_u32 s0, s9, s0
	s_addc_u32 s1, s18, s1
	s_add_i32 s12, s8, s10
	s_ashr_i32 s13, s12, 31
	s_add_i32 s15, s15, s14
	s_add_i32 s10, s10, s19
	s_waitcnt vmcnt(15)
	ds_write2_b32 v124, v0, v1 offset1:1
	ds_write2_b32 v124, v2, v3 offset0:2 offset1:3
	s_waitcnt vmcnt(12)
	ds_write2_b32 v139, v4, v5 offset1:1
	ds_write2_b32 v140, v6, v7 offset1:1
	s_waitcnt vmcnt(10)
	ds_write2_b32 v141, v8, v9 offset1:1
	ds_write2_b32 v142, v10, v11 offset1:1
	s_waitcnt vmcnt(8)
	ds_write2_b32 v143, v12, v13 offset1:1
	ds_write2_b32 v144, v14, v15 offset1:1
	s_waitcnt vmcnt(7)
	ds_write2_b32 v145, v16, v17 offset1:1
	ds_write2_b32 v146, v18, v19 offset1:1
	s_waitcnt vmcnt(6)
	ds_write2_b32 v147, v20, v21 offset1:1
	ds_write2_b32 v32, v22, v23 offset0:2 offset1:3
	s_waitcnt vmcnt(5)
	ds_write2_b32 v125, v24, v25 offset1:1
	ds_write2_b32 v126, v26, v27 offset1:1
	s_waitcnt vmcnt(4)
	ds_write2_b32 v127, v28, v29 offset1:1
	ds_write2_b32 v128, v30, v31 offset1:1
	s_waitcnt vmcnt(3)
	ds_write2_b32 v129, v70, v71 offset1:1
	ds_write2_b32 v130, v72, v73 offset1:1
	s_waitcnt vmcnt(2)
	ds_write2_b32 v131, v74, v75 offset1:1
	ds_write2_b32 v132, v76, v77 offset1:1
	s_waitcnt vmcnt(1)
	ds_write2_b32 v133, v78, v79 offset1:1
	ds_write2_b32 v134, v80, v81 offset1:1
	s_waitcnt vmcnt(0)
	ds_write2_b32 v135, v104, v105 offset1:1
	ds_write2_b32 v136, v106, v107 offset1:1
	ds_write2_b32 v137, v108, v109 offset1:1
	ds_write2_b32 v138, v110, v111 offset1:1
	v_add_u32_e32 v0, 0xe700, v95
	ds_write2_b32 v0, v112, v113 offset1:1
	v_add_u32_e32 v0, 0xe708, v95
	ds_write2_b32 v0, v114, v115 offset1:1
	v_add_u32_e32 v0, 0xe700, v96
	ds_write2_b32 v0, v116, v117 offset1:1
	v_add_u32_e32 v0, 0xe708, v96
	ds_write2_b32 v0, v118, v119 offset1:1
	v_add_u32_e32 v0, 0xe700, v97
	ds_write2_b32 v0, v120, v121 offset1:1
	v_add_u32_e32 v0, 0xe708, v97
	ds_write2_b32 v0, v122, v123 offset1:1
	s_waitcnt lgkmcnt(0)
	s_barrier
	global_load_dwordx4 v[0:3], v33, s[0:1]
	global_load_dwordx4 v[4:7], v33, s[0:1] offset:16
	global_load_dwordx4 v[8:11], v33, s[0:1] offset:32
	global_load_dwordx4 v[12:15], v33, s[0:1] offset:48
	v_add_u32_e32 v26, s16, v86
	v_add_u32_e32 v30, s16, v87
	v_add_u32_e32 v123, 0xc68c, v84
	s_waitcnt vmcnt(3)
	v_ffbh_u32_e32 v16, v1
	v_ffbh_u32_e32 v17, v3
	s_waitcnt vmcnt(2)
	v_ffbh_u32_e32 v18, v5
	s_waitcnt vmcnt(1)
	v_ffbh_u32_e32 v20, v9
	v_min_u32_e32 v16, 32, v16
	v_min_u32_e32 v17, 32, v17
	v_min_u32_e32 v18, 32, v18
	v_min_u32_e32 v20, 32, v20
	v_lshlrev_b64 v[0:1], v16, v[0:1]
	v_lshlrev_b64 v[2:3], v17, v[2:3]
	v_lshlrev_b64 v[4:5], v18, v[4:5]
	v_lshlrev_b64 v[8:9], v20, v[8:9]
	v_ffbh_u32_e32 v21, v11
	v_min_u32_e32 v0, 1, v0
	v_min_u32_e32 v2, 1, v2
	v_min_u32_e32 v4, 1, v4
	v_min_u32_e32 v8, 1, v8
	v_min_u32_e32 v21, 32, v21
	v_or_b32_e32 v0, v1, v0
	v_or_b32_e32 v1, v3, v2
	v_or_b32_e32 v2, v5, v4
	v_or_b32_e32 v4, v9, v8
	v_ffbh_u32_e32 v19, v7
	s_waitcnt vmcnt(0)
	v_ffbh_u32_e32 v23, v15
	v_lshlrev_b64 v[10:11], v21, v[10:11]
	v_cvt_f32_u32_e32 v4, v4
	v_ffbh_u32_e32 v22, v13
	v_min_u32_e32 v19, 32, v19
	v_min_u32_e32 v23, 32, v23
	v_min_u32_e32 v10, 1, v10
	v_min_u32_e32 v22, 32, v22
	v_lshlrev_b64 v[6:7], v19, v[6:7]
	v_lshlrev_b64 v[14:15], v23, v[14:15]
	v_or_b32_e32 v5, v11, v10
	v_sub_u32_e32 v20, 32, v20
	v_lshlrev_b64 v[12:13], v22, v[12:13]
	v_min_u32_e32 v6, 1, v6
	v_min_u32_e32 v14, 1, v14
	v_cvt_f32_u32_e32 v5, v5
	v_min_u32_e32 v12, 1, v12
	v_or_b32_e32 v3, v7, v6
	v_or_b32_e32 v7, v15, v14
	v_ldexp_f32 v4, v4, v20
	v_or_b32_e32 v6, v13, v12
	v_cvt_f32_u32_e32 v0, v0
	v_cvt_f32_u32_e32 v1, v1
	v_cvt_f32_u32_e32 v2, v2
	v_cvt_f32_u32_e32 v3, v3
	v_mul_f32_e32 v107, 0x2f800000, v4
	v_cvt_f32_u32_e32 v4, v7
	v_sub_u32_e32 v21, 32, v21
	v_cvt_f32_u32_e32 v6, v6
	v_ldexp_f32 v5, v5, v21
	v_sub_u32_e32 v16, 32, v16
	v_sub_u32_e32 v17, 32, v17
	v_sub_u32_e32 v18, 32, v18
	v_sub_u32_e32 v19, 32, v19
	v_mul_f32_e32 v106, 0x2f800000, v5
	v_sub_u32_e32 v5, 32, v23
	v_sub_u32_e32 v22, 32, v22
	v_ldexp_f32 v0, v0, v16
	v_ldexp_f32 v1, v1, v17
	v_ldexp_f32 v2, v2, v18
	v_ldexp_f32 v3, v3, v19
	v_ldexp_f32 v4, v4, v5
	v_ldexp_f32 v6, v6, v22
	v_mul_f32_e32 v174, 0x2f800000, v0
	v_mul_f32_e32 v155, 0x2f800000, v1
	v_mul_f32_e32 v122, 0x2f800000, v2
	v_mul_f32_e32 v108, 0x2f800000, v3
	ds_read2_b64 v[0:3], v84 offset1:1
	ds_read2_b32 v[70:71], v84 offset0:33 offset1:34
	v_mul_f32_e32 v104, 0x2f800000, v4
	v_add_u32_e32 v4, 0x4200, v84
	v_add_u32_e32 v8, 0x4284, v84
	v_mul_f32_e32 v105, 0x2f800000, v6
	ds_read2_b64 v[4:7], v4 offset1:1
	ds_read2_b32 v[72:73], v8 offset1:1
	ds_read2_b32 v[74:75], v84 offset0:35 offset1:36
	v_add_u32_e32 v14, 0x8484, v84
	v_add_u32_e32 v8, 0x8400, v84
	ds_read2_b32 v[110:111], v14 offset1:1
	ds_read2_b32 v[116:117], v26 offset1:1
	ds_read2_b64 v[8:11], v8 offset1:1
	s_waitcnt lgkmcnt(6)
	v_lshlrev_b32_e32 v173, 16, v70
	s_waitcnt lgkmcnt(4)
	v_lshlrev_b32_e32 v202, 16, v72
	v_lshlrev_b32_e32 v172, 16, v0
	v_mul_f32_e32 v12, v173, v173
	v_lshlrev_b32_e32 v197, 16, v4
	v_mul_f32_e32 v13, v202, v202
	v_fmac_f32_e32 v12, v172, v172
	v_fmac_f32_e32 v13, v197, v197
	v_add_u32_e32 v18, 0xc684, v84
	v_add_u32_e32 v22, s16, v85
	v_add_f32_e32 v16, v12, v13
	v_add_u32_e32 v12, 0xc600, v84
	ds_read2_b32 v[112:113], v18 offset1:1
	ds_read2_b32 v[114:115], v22 offset1:1
	s_waitcnt lgkmcnt(4)
	v_lshlrev_b32_e32 v203, 16, v110
	ds_read2_b64 v[12:15], v12 offset1:1
	s_waitcnt lgkmcnt(3)
	v_lshlrev_b32_e32 v198, 16, v8
	v_mul_f32_e32 v17, v203, v203
	v_fmac_f32_e32 v17, v198, v198
	v_add_f32_e32 v20, v16, v17
	ds_read2_b64 v[16:19], v98 offset1:1
	ds_read2_b32 v[118:119], v30 offset1:1
	s_waitcnt lgkmcnt(4)
	v_lshlrev_b32_e32 v201, 16, v112
	s_waitcnt lgkmcnt(2)
	v_lshlrev_b32_e32 v199, 16, v12
	v_mul_f32_e32 v21, v201, v201
	v_lshlrev_b32_e32 v200, 16, v114
	v_fmac_f32_e32 v21, v199, v199
	s_waitcnt lgkmcnt(1)
	v_lshlrev_b32_e32 v195, 16, v16
	v_mul_f32_e32 v25, v200, v200
	v_add_f32_e32 v24, v20, v21
	ds_read2_b64 v[20:23], v99 offset1:1
	v_fmac_f32_e32 v25, v195, v195
	v_add_f32_e32 v28, v24, v25
	ds_read2_b64 v[24:27], v100 offset1:1
	v_and_b32_e32 v190, 0xffff0000, v70
	v_and_b32_e32 v188, 0xffff0000, v72
	v_and_b32_e32 v189, 0xffff0000, v0
	v_mul_f32_e32 v0, v190, v190
	v_and_b32_e32 v187, 0xffff0000, v4
	v_mul_f32_e32 v4, v188, v188
	v_lshlrev_b32_e32 v196, 16, v116
	v_fmac_f32_e32 v0, v189, v189
	v_fmac_f32_e32 v4, v187, v187
	v_and_b32_e32 v186, 0xffff0000, v110
	s_waitcnt lgkmcnt(1)
	v_lshlrev_b32_e32 v193, 16, v20
	v_mul_f32_e32 v29, v196, v196
	v_lshlrev_b32_e32 v194, 16, v118
	v_add_f32_e32 v0, v0, v4
	v_and_b32_e32 v185, 0xffff0000, v8
	v_mul_f32_e32 v4, v186, v186
	v_fmac_f32_e32 v29, v193, v193
	s_waitcnt lgkmcnt(0)
	v_lshlrev_b32_e32 v192, 16, v24
	v_mul_f32_e32 v77, v194, v194
	v_fmac_f32_e32 v4, v185, v185
	v_and_b32_e32 v184, 0xffff0000, v112
	v_add_f32_e32 v76, v28, v29
	v_fmac_f32_e32 v77, v192, v192
	v_add_f32_e32 v0, v0, v4
	v_and_b32_e32 v183, 0xffff0000, v12
	v_mul_f32_e32 v4, v184, v184
	v_add_f32_e32 v109, v76, v77
	v_add_u32_e32 v76, s16, v88
	v_fmac_f32_e32 v4, v183, v183
	v_and_b32_e32 v182, 0xffff0000, v114
	ds_read2_b64 v[28:31], v101 offset1:1
	ds_read2_b32 v[120:121], v76 offset1:1
	v_add_f32_e32 v0, v0, v4
	v_and_b32_e32 v181, 0xffff0000, v16
	v_mul_f32_e32 v4, v182, v182
	v_fmac_f32_e32 v4, v181, v181
	v_and_b32_e32 v180, 0xffff0000, v116
	v_add_f32_e32 v0, v0, v4
	v_and_b32_e32 v179, 0xffff0000, v20
	v_mul_f32_e32 v4, v180, v180
	v_fmac_f32_e32 v4, v179, v179
	v_and_b32_e32 v178, 0xffff0000, v118
	v_add_f32_e32 v0, v0, v4
	v_and_b32_e32 v177, 0xffff0000, v24
	v_mul_f32_e32 v4, v178, v178
	v_fmac_f32_e32 v4, v177, v177
	s_waitcnt lgkmcnt(0)
	v_and_b32_e32 v176, 0xffff0000, v120
	v_add_f32_e32 v0, v0, v4
	v_and_b32_e32 v175, 0xffff0000, v28
	v_mul_f32_e32 v4, v176, v176
	v_fmac_f32_e32 v4, v175, v175
	v_lshlrev_b32_e32 v171, 16, v71
	v_lshlrev_b32_e32 v169, 16, v73
	v_add_f32_e32 v210, v0, v4
	v_lshlrev_b32_e32 v170, 16, v1
	v_mul_f32_e32 v0, v171, v171
	v_lshlrev_b32_e32 v168, 16, v5
	v_mul_f32_e32 v4, v169, v169
	v_fmac_f32_e32 v0, v170, v170
	v_fmac_f32_e32 v4, v168, v168
	v_lshlrev_b32_e32 v167, 16, v111
	v_add_f32_e32 v0, v0, v4
	v_lshlrev_b32_e32 v166, 16, v9
	v_mul_f32_e32 v4, v167, v167
	v_fmac_f32_e32 v4, v166, v166
	v_lshlrev_b32_e32 v165, 16, v113
	v_add_f32_e32 v0, v0, v4
	v_lshlrev_b32_e32 v164, 16, v13
	v_mul_f32_e32 v4, v165, v165
	v_fmac_f32_e32 v4, v164, v164
	v_lshlrev_b32_e32 v163, 16, v115
	v_add_f32_e32 v0, v0, v4
	v_lshlrev_b32_e32 v162, 16, v17
	v_mul_f32_e32 v4, v163, v163
	v_fmac_f32_e32 v4, v162, v162
	v_lshlrev_b32_e32 v161, 16, v117
	v_add_f32_e32 v0, v0, v4
	v_lshlrev_b32_e32 v160, 16, v21
	v_mul_f32_e32 v4, v161, v161
	v_fmac_f32_e32 v4, v160, v160
	v_lshlrev_b32_e32 v159, 16, v119
	v_add_f32_e32 v0, v0, v4
	v_lshlrev_b32_e32 v158, 16, v25
	v_mul_f32_e32 v4, v159, v159
	v_fmac_f32_e32 v4, v158, v158
	v_lshlrev_b32_e32 v157, 16, v121
	v_add_f32_e32 v0, v0, v4
	v_lshlrev_b32_e32 v156, 16, v29
	v_mul_f32_e32 v4, v157, v157
	v_fmac_f32_e32 v4, v156, v156
	v_and_b32_e32 v154, 0xffff0000, v71
	v_and_b32_e32 v152, 0xffff0000, v73
	v_add_f32_e32 v211, v0, v4
	v_and_b32_e32 v153, 0xffff0000, v1
	v_mul_f32_e32 v0, v154, v154
	v_and_b32_e32 v151, 0xffff0000, v5
	v_mul_f32_e32 v1, v152, v152
	v_fmac_f32_e32 v0, v153, v153
	v_fmac_f32_e32 v1, v151, v151
	v_and_b32_e32 v150, 0xffff0000, v111
	v_add_f32_e32 v0, v0, v1
	v_and_b32_e32 v149, 0xffff0000, v9
	v_mul_f32_e32 v1, v150, v150
	v_fmac_f32_e32 v1, v149, v149
	v_and_b32_e32 v148, 0xffff0000, v113
	v_add_f32_e32 v0, v0, v1
	v_and_b32_e32 v147, 0xffff0000, v13
	v_mul_f32_e32 v1, v148, v148
	v_fmac_f32_e32 v1, v147, v147
	v_and_b32_e32 v146, 0xffff0000, v115
	v_add_f32_e32 v0, v0, v1
	v_and_b32_e32 v145, 0xffff0000, v17
	v_mul_f32_e32 v1, v146, v146
	v_fmac_f32_e32 v1, v145, v145
	v_and_b32_e32 v144, 0xffff0000, v117
	v_add_f32_e32 v0, v0, v1
	v_and_b32_e32 v143, 0xffff0000, v21
	v_mul_f32_e32 v1, v144, v144
	v_add_u32_e32 v76, 0x428c, v84
	v_add_u32_e32 v77, 0x848c, v84
	v_fmac_f32_e32 v1, v143, v143
	v_and_b32_e32 v142, 0xffff0000, v119
	ds_read2_b32 v[80:81], v76 offset1:1
	ds_read2_b32 v[78:79], v77 offset1:1
	ds_read2_b32 v[76:77], v123 offset1:1
	v_add_f32_e32 v0, v0, v1
	v_and_b32_e32 v141, 0xffff0000, v25
	v_mul_f32_e32 v1, v142, v142
	v_fmac_f32_e32 v1, v141, v141
	v_and_b32_e32 v140, 0xffff0000, v121
	v_add_f32_e32 v0, v0, v1
	v_and_b32_e32 v139, 0xffff0000, v29
	v_mul_f32_e32 v1, v140, v140
	v_fmac_f32_e32 v1, v139, v139
	v_lshlrev_b32_e32 v133, 16, v74
	s_waitcnt lgkmcnt(2)
	v_lshlrev_b32_e32 v131, 16, v80
	v_add_f32_e32 v212, v0, v1
	v_lshlrev_b32_e32 v132, 16, v2
	v_mul_f32_e32 v0, v133, v133
	v_lshlrev_b32_e32 v130, 16, v6
	v_mul_f32_e32 v1, v131, v131
	v_fmac_f32_e32 v0, v132, v132
	v_fmac_f32_e32 v1, v130, v130
	s_waitcnt lgkmcnt(1)
	v_lshlrev_b32_e32 v129, 16, v78
	v_add_f32_e32 v0, v0, v1
	v_lshlrev_b32_e32 v128, 16, v10
	v_mul_f32_e32 v1, v129, v129
	v_fmac_f32_e32 v1, v128, v128
	s_waitcnt lgkmcnt(0)
	v_lshlrev_b32_e32 v127, 16, v76
	v_add_f32_e32 v0, v0, v1
	v_lshlrev_b32_e32 v126, 16, v14
	v_mul_f32_e32 v1, v127, v127
	v_fmac_f32_e32 v1, v126, v126
	v_add_f32_e32 v8, v0, v1
	v_add_u32_e32 v0, s17, v85
	ds_read2_b32 v[0:1], v0 offset1:1
	v_and_b32_e32 v121, 0xffff0000, v74
	v_and_b32_e32 v119, 0xffff0000, v80
	v_lshlrev_b32_e32 v204, 16, v120
	v_and_b32_e32 v120, 0xffff0000, v2
	v_mul_f32_e32 v2, v121, v121
	v_and_b32_e32 v118, 0xffff0000, v6
	v_mul_f32_e32 v6, v119, v119
	v_fmac_f32_e32 v2, v120, v120
	v_fmac_f32_e32 v6, v118, v118
	v_and_b32_e32 v117, 0xffff0000, v78
	v_add_u32_e32 v4, s17, v86
	v_add_f32_e32 v2, v2, v6
	v_and_b32_e32 v116, 0xffff0000, v10
	v_mul_f32_e32 v6, v117, v117
	v_add_u32_e32 v9, s17, v87
	v_add_u32_e32 v12, s17, v88
	ds_read2_b32 v[4:5], v4 offset1:1
	ds_read2_b32 v[206:207], v9 offset1:1
	ds_read2_b32 v[208:209], v12 offset1:1
	v_fmac_f32_e32 v6, v116, v116
	v_and_b32_e32 v115, 0xffff0000, v76
	v_add_f32_e32 v2, v2, v6
	v_and_b32_e32 v114, 0xffff0000, v14
	v_mul_f32_e32 v6, v115, v115
	s_waitcnt lgkmcnt(3)
	v_and_b32_e32 v113, 0xffff0000, v0
	v_lshlrev_b32_e32 v138, 16, v0
	v_fmac_f32_e32 v6, v114, v114
	v_and_b32_e32 v112, 0xffff0000, v18
	v_mul_f32_e32 v0, v113, v113
	v_lshlrev_b32_e32 v191, 16, v28
	v_mul_f32_e32 v123, v204, v204
	v_add_f32_e32 v2, v2, v6
	v_fmac_f32_e32 v0, v112, v112
	s_waitcnt lgkmcnt(2)
	v_and_b32_e32 v111, 0xffff0000, v4
	v_fmac_f32_e32 v123, v191, v191
	v_add_f32_e32 v0, v2, v0
	v_and_b32_e32 v110, 0xffff0000, v22
	v_mul_f32_e32 v2, v111, v111
	v_add_f32_e32 v205, v109, v123
	v_fmac_f32_e32 v2, v110, v110
	s_waitcnt lgkmcnt(1)
	v_and_b32_e32 v109, 0xffff0000, v206
	v_add_f32_e32 v0, v0, v2
	v_and_b32_e32 v80, 0xffff0000, v26
	v_mul_f32_e32 v2, v109, v109
	v_fmac_f32_e32 v2, v80, v80
	s_waitcnt lgkmcnt(0)
	v_and_b32_e32 v78, 0xffff0000, v208
	v_add_f32_e32 v0, v0, v2
	v_and_b32_e32 v76, 0xffff0000, v30
	v_mul_f32_e32 v2, v78, v78
	v_fmac_f32_e32 v2, v76, v76
	v_lshlrev_b32_e32 v74, 16, v75
	v_lshlrev_b32_e32 v72, 16, v81
	v_lshlrev_b32_e32 v135, 16, v206
	v_add_f32_e32 v206, v0, v2
	v_lshlrev_b32_e32 v73, 16, v3
	v_mul_f32_e32 v0, v74, v74
	v_lshlrev_b32_e32 v71, 16, v7
	v_mul_f32_e32 v2, v72, v72
	v_fmac_f32_e32 v0, v73, v73
	v_fmac_f32_e32 v2, v71, v71
	v_lshlrev_b32_e32 v70, 16, v79
	v_lshlrev_b32_e32 v124, 16, v30
	v_add_f32_e32 v0, v0, v2
	v_lshlrev_b32_e32 v30, 16, v11
	v_mul_f32_e32 v2, v70, v70
	v_fmac_f32_e32 v2, v30, v30
	v_lshlrev_b32_e32 v29, 16, v77
	v_add_f32_e32 v0, v0, v2
	v_lshlrev_b32_e32 v28, 16, v15
	v_mul_f32_e32 v2, v29, v29
	v_lshlrev_b32_e32 v134, 16, v26
	v_fmac_f32_e32 v2, v28, v28
	v_lshlrev_b32_e32 v26, 16, v1
	v_add_f32_e32 v0, v0, v2
	v_lshlrev_b32_e32 v25, 16, v19
	v_mul_f32_e32 v2, v26, v26
	v_fmac_f32_e32 v2, v25, v25
	v_lshlrev_b32_e32 v24, 16, v5
	v_lshlrev_b32_e32 v136, 16, v22
	v_add_f32_e32 v0, v0, v2
	v_lshlrev_b32_e32 v22, 16, v23
	v_mul_f32_e32 v2, v24, v24
	v_lshlrev_b32_e32 v123, 16, v18
	v_mul_f32_e32 v9, v138, v138
	v_fmac_f32_e32 v2, v22, v22
	v_lshlrev_b32_e32 v21, 16, v207
	v_fmac_f32_e32 v9, v123, v123
	v_lshlrev_b32_e32 v137, 16, v4
	v_add_f32_e32 v0, v0, v2
	v_lshlrev_b32_e32 v20, 16, v27
	v_mul_f32_e32 v2, v21, v21
	v_add_f32_e32 v8, v8, v9
	v_mul_f32_e32 v9, v137, v137
	v_fmac_f32_e32 v2, v20, v20
	v_lshlrev_b32_e32 v18, 16, v209
	v_fmac_f32_e32 v9, v136, v136
	v_add_f32_e32 v0, v0, v2
	v_lshlrev_b32_e32 v17, 16, v31
	v_mul_f32_e32 v2, v18, v18
	v_add_f32_e32 v8, v8, v9
	v_mul_f32_e32 v9, v135, v135
	v_fmac_f32_e32 v2, v17, v17
	v_and_b32_e32 v16, 0xffff0000, v75
	v_and_b32_e32 v13, 0xffff0000, v81
	v_fmac_f32_e32 v9, v134, v134
	v_lshlrev_b32_e32 v125, 16, v208
	v_add_f32_e32 v208, v0, v2
	v_and_b32_e32 v14, 0xffff0000, v3
	v_mul_f32_e32 v0, v16, v16
	v_and_b32_e32 v12, 0xffff0000, v7
	v_mul_f32_e32 v2, v13, v13
	v_add_f32_e32 v8, v8, v9
	v_mul_f32_e32 v9, v125, v125
	v_fmac_f32_e32 v0, v14, v14
	v_fmac_f32_e32 v2, v12, v12
	v_and_b32_e32 v10, 0xffff0000, v11
	v_and_b32_e32 v11, 0xffff0000, v79
	v_fmac_f32_e32 v9, v124, v124
	v_add_f32_e32 v0, v0, v2
	v_mul_f32_e32 v2, v11, v11
	v_add_f32_e32 v213, v8, v9
	v_fmac_f32_e32 v2, v10, v10
	v_and_b32_e32 v9, 0xffff0000, v77
	v_add_f32_e32 v0, v0, v2
	v_and_b32_e32 v8, 0xffff0000, v15
	v_mul_f32_e32 v2, v9, v9
	v_and_b32_e32 v7, 0xffff0000, v1
	v_fmac_f32_e32 v2, v8, v8
	v_and_b32_e32 v6, 0xffff0000, v19
	v_mul_f32_e32 v1, v7, v7
	v_add_f32_e32 v0, v0, v2
	v_fmac_f32_e32 v1, v6, v6
	v_and_b32_e32 v5, 0xffff0000, v5
	v_add_f32_e32 v0, v0, v1
	v_and_b32_e32 v4, 0xffff0000, v23
	v_mul_f32_e32 v1, v5, v5
	v_fmac_f32_e32 v1, v4, v4
	v_and_b32_e32 v3, 0xffff0000, v207
	v_add_f32_e32 v0, v0, v1
	v_and_b32_e32 v2, 0xffff0000, v27
	v_mul_f32_e32 v1, v3, v3
	v_fmac_f32_e32 v1, v2, v2
	v_add_f32_e32 v15, v0, v1
	v_and_b32_e32 v0, 0xffff0000, v31
	ds_bpermute_b32 v23, v89, v205
	ds_bpermute_b32 v27, v89, v210
	ds_bpermute_b32 v31, v89, v211
	v_and_b32_e32 v1, 0xffff0000, v209
	ds_bpermute_b32 v77, v89, v206
	v_mul_f32_e32 v19, v1, v1
	v_fmac_f32_e32 v19, v0, v0
	ds_bpermute_b32 v75, v89, v213
	v_add_f32_e32 v15, v15, v19
	ds_bpermute_b32 v79, v89, v208
	s_waitcnt lgkmcnt(5)
	v_add_f32_e32 v19, v205, v23
	s_waitcnt lgkmcnt(4)
	v_add_f32_e32 v23, v210, v27
	s_waitcnt lgkmcnt(3)
	v_add_f32_e32 v27, v211, v31
	ds_bpermute_b32 v81, v89, v15
	ds_bpermute_b32 v31, v89, v212
	s_waitcnt lgkmcnt(4)
	v_add_f32_e32 v77, v206, v77
	ds_bpermute_b32 v206, v90, v27
	s_waitcnt lgkmcnt(4)
	v_add_f32_e32 v75, v213, v75
	ds_bpermute_b32 v205, v90, v23
	s_waitcnt lgkmcnt(4)
	v_add_f32_e32 v79, v208, v79
	ds_bpermute_b32 v208, v90, v75
	s_waitcnt lgkmcnt(4)
	v_add_f32_e32 v15, v15, v81
	s_waitcnt lgkmcnt(3)
	v_add_f32_e32 v31, v212, v31
	ds_bpermute_b32 v81, v90, v19
	s_waitcnt lgkmcnt(3)
	v_add_f32_e32 v27, v27, v206
	ds_bpermute_b32 v206, v90, v15
	ds_bpermute_b32 v207, v90, v31
	s_waitcnt lgkmcnt(4)
	v_add_f32_e32 v23, v23, v205
	ds_bpermute_b32 v205, v90, v79
	s_waitcnt lgkmcnt(4)
	v_add_f32_e32 v75, v75, v208
	ds_bpermute_b32 v208, v91, v23
	s_waitcnt lgkmcnt(4)
	v_add_f32_e32 v19, v19, v81
	ds_bpermute_b32 v81, v90, v77
	s_waitcnt lgkmcnt(4)
	v_add_f32_e32 v15, v15, v206
	ds_bpermute_b32 v206, v91, v75
	s_waitcnt lgkmcnt(4)
	v_add_f32_e32 v31, v31, v207
	ds_bpermute_b32 v207, v91, v19
	s_waitcnt lgkmcnt(4)
	v_add_f32_e32 v79, v79, v205
	ds_bpermute_b32 v205, v91, v31
	s_waitcnt lgkmcnt(4)
	v_add_f32_e32 v23, v23, v208
	ds_bpermute_b32 v208, v91, v79
	s_waitcnt lgkmcnt(4)
	v_add_f32_e32 v77, v77, v81
	ds_bpermute_b32 v81, v91, v27
	s_waitcnt lgkmcnt(4)
	v_add_f32_e32 v75, v75, v206
	ds_bpermute_b32 v206, v92, v23
	s_waitcnt lgkmcnt(4)
	v_add_f32_e32 v19, v19, v207
	ds_bpermute_b32 v207, v91, v77
	s_waitcnt lgkmcnt(4)
	v_add_f32_e32 v31, v31, v205
	ds_bpermute_b32 v205, v92, v19
	s_waitcnt lgkmcnt(4)
	v_add_f32_e32 v79, v79, v208
	ds_bpermute_b32 v208, v92, v31
	s_waitcnt lgkmcnt(4)
	v_add_f32_e32 v27, v27, v81
	s_waitcnt lgkmcnt(3)
	v_add_f32_e32 v23, v23, v206
	ds_bpermute_b32 v206, v92, v79
	s_waitcnt lgkmcnt(3)
	v_add_f32_e32 v77, v77, v207
	ds_bpermute_b32 v81, v91, v15
	ds_bpermute_b32 v207, v92, v27
	s_waitcnt lgkmcnt(4)
	v_add_f32_e32 v19, v19, v205
	ds_bpermute_b32 v205, v92, v77
	s_waitcnt lgkmcnt(4)
	v_add_f32_e32 v31, v31, v208
	ds_bpermute_b32 v208, v93, v19
	s_waitcnt lgkmcnt(4)
	v_add_f32_e32 v79, v79, v206
	ds_bpermute_b32 v206, v93, v31
	s_waitcnt lgkmcnt(4)
	v_add_f32_e32 v15, v15, v81
	s_waitcnt lgkmcnt(3)
	v_add_f32_e32 v27, v27, v207
	ds_bpermute_b32 v81, v92, v75
	ds_bpermute_b32 v207, v92, v15
	s_waitcnt lgkmcnt(4)
	v_add_f32_e32 v77, v77, v205
	ds_bpermute_b32 v205, v93, v27
	s_waitcnt lgkmcnt(4)
	v_add_f32_e32 v19, v19, v208
	ds_bpermute_b32 v208, v93, v77
	s_waitcnt lgkmcnt(4)
	v_add_f32_e32 v31, v31, v206
	ds_bpermute_b32 v206, v94, v19
	s_waitcnt lgkmcnt(4)
	v_add_f32_e32 v75, v75, v81
	s_waitcnt lgkmcnt(3)
	v_add_f32_e32 v15, v15, v207
	ds_bpermute_b32 v207, v93, v75
	s_waitcnt lgkmcnt(3)
	v_add_f32_e32 v27, v27, v205
	ds_bpermute_b32 v81, v93, v23
	s_waitcnt lgkmcnt(3)
	v_add_f32_e32 v77, v77, v208
	ds_bpermute_b32 v205, v93, v15
	ds_bpermute_b32 v208, v94, v27
	s_waitcnt lgkmcnt(4)
	v_add_f32_e32 v19, v19, v206
	v_fmamk_f32 v19, v19, 0x3a800000, v102
	s_waitcnt lgkmcnt(3)
	v_add_f32_e32 v75, v75, v207
	v_mul_f32_e32 v206, 0x4f800000, v19
	v_cmp_gt_f32_e32 vcc, s23, v19
	s_waitcnt lgkmcnt(2)
	v_add_f32_e32 v23, v23, v81
	s_waitcnt lgkmcnt(1)
	v_add_f32_e32 v15, v15, v205
	s_waitcnt lgkmcnt(0)
	v_add_f32_e32 v205, v27, v208
	ds_bpermute_b32 v27, v94, v75
	v_cndmask_b32_e32 v19, v19, v206, vcc
	ds_bpermute_b32 v81, v93, v79
	ds_bpermute_b32 v207, v94, v23
	v_sqrt_f32_e32 v206, v19
	s_waitcnt lgkmcnt(2)
	v_add_f32_e32 v27, v75, v27
	v_fmamk_f32 v174, v174, 0x3a800000, v102
	s_waitcnt lgkmcnt(1)
	v_add_f32_e32 v79, v79, v81
	v_add_u32_e32 v75, -1, v206
	s_waitcnt lgkmcnt(0)
	v_add_f32_e32 v81, v23, v207
	v_fma_f32 v207, -v75, v206, v19
	v_cmp_ge_f32_e64 s[4:5], 0, v207
	v_add_u32_e32 v207, 1, v206
	v_mul_f32_e32 v210, 0x4f800000, v174
	v_cndmask_b32_e64 v75, v206, v75, s[4:5]
	v_fma_f32 v206, -v207, v206, v19
	v_cmp_lt_f32_e64 s[4:5], 0, v206
	ds_bpermute_b32 v23, v94, v31
	v_fmamk_f32 v155, v155, 0x3a800000, v102
	v_cndmask_b32_e64 v75, v75, v207, s[4:5]
	v_mul_f32_e32 v206, 0x37800000, v75
	v_cndmask_b32_e32 v75, v75, v206, vcc
	v_cmp_class_f32_e32 vcc, v19, v103
	v_cmp_gt_f32_e64 s[4:5], s23, v174
	s_waitcnt lgkmcnt(0)
	v_add_f32_e32 v31, v31, v23
	v_cndmask_b32_e32 v19, v75, v19, vcc
	v_div_scale_f32 v75, s[0:1], v19, v19, 1.0
	v_rcp_f32_e32 v206, v75
	v_cndmask_b32_e64 v174, v174, v210, s[4:5]
	v_sqrt_f32_e32 v210, v174
	ds_bpermute_b32 v23, v94, v77
	v_fma_f32 v208, -v75, v206, 1.0
	v_fmac_f32_e32 v206, v208, v206
	v_div_scale_f32 v208, vcc, 1.0, v19, 1.0
	v_mul_f32_e32 v209, v208, v206
	v_fma_f32 v211, -v75, v209, v208
	v_fmac_f32_e32 v209, v211, v206
	v_fma_f32 v75, -v75, v209, v208
	v_add_u32_e32 v208, -1, v210
	v_fma_f32 v211, -v208, v210, v174
	v_cmp_ge_f32_e64 s[6:7], 0, v211
	v_add_u32_e32 v211, 1, v210
	v_div_fmas_f32 v75, v75, v206, v209
	v_cndmask_b32_e64 v208, v210, v208, s[6:7]
	v_fma_f32 v210, -v211, v210, v174
	v_cmp_lt_f32_e64 s[6:7], 0, v210
	v_div_fixup_f32 v75, v75, v19, 1.0
	s_waitcnt lgkmcnt(0)
	v_add_f32_e32 v23, v77, v23
	v_cndmask_b32_e64 v208, v208, v211, s[6:7]
	v_mul_f32_e32 v210, 0x37800000, v208
	v_cndmask_b32_e64 v208, v208, v210, s[4:5]
	v_cmp_class_f32_e64 s[4:5], v174, v103
	ds_bpermute_b32 v77, v94, v79
	ds_bpermute_b32 v207, v94, v15
	v_cndmask_b32_e64 v174, v208, v174, s[4:5]
	v_div_scale_f32 v208, s[0:1], v174, v174, 1.0
	v_rcp_f32_e32 v210, v208
	s_waitcnt lgkmcnt(0)
	v_add_f32_e32 v15, v15, v207
	v_fmamk_f32 v122, v122, 0x3a800000, v102
	v_fmamk_f32 v31, v31, 0x3a800000, v102
	v_fma_f32 v19, -v208, v210, 1.0
	v_fmac_f32_e32 v210, v19, v210
	v_div_scale_f32 v19, vcc, 1.0, v174, 1.0
	v_mul_f32_e32 v206, v19, v210
	v_fma_f32 v209, -v208, v206, v19
	v_fmac_f32_e32 v206, v209, v210
	v_fma_f32 v19, -v208, v206, v19
	v_div_fmas_f32 v19, v19, v210, v206
	v_div_fixup_f32 v174, v19, v174, 1.0
	v_div_scale_f32 v206, s[0:1], v174, v174, v75
	v_rcp_f32_e32 v208, v206
	v_add_f32_e32 v19, v79, v77
	s_lshl_b64 s[0:1], s[12:13], 12
	v_fmamk_f32 v108, v108, 0x3a800000, v102
	v_fma_f32 v77, -v206, v208, 1.0
	v_fmac_f32_e32 v208, v77, v208
	v_div_scale_f32 v77, vcc, v75, v174, v75
	v_mul_f32_e32 v79, v77, v208
	v_fma_f32 v207, -v206, v79, v77
	v_fmac_f32_e32 v79, v207, v208
	v_fma_f32 v77, -v206, v79, v77
	v_div_fmas_f32 v77, v77, v208, v79
	v_div_fixup_f32 v75, v77, v174, v75
	v_mul_f32_e32 v77, v75, v172
	v_mul_f32_e32 v79, v75, v173
	v_bfe_u32 v172, v77, 16, 1
	v_add3_u32 v77, v77, v172, s24
	v_bfe_u32 v172, v79, 16, 1
	v_lshrrev_b32_e32 v77, 16, v77
	v_add3_u32 v79, v79, v172, s24
	v_lshl_add_u64 v[206:207], v[68:69], 0, s[0:1]
	v_and_or_b32 v77, v79, s22, v77
	global_store_dword v[206:207], v77, off offset:2048 nt
	v_mul_f32_e32 v77, v75, v197
	v_mul_f32_e32 v79, v75, v202
	v_bfe_u32 v172, v77, 16, 1
	v_add3_u32 v77, v77, v172, s24
	v_bfe_u32 v172, v79, 16, 1
	v_lshrrev_b32_e32 v77, 16, v77
	v_add3_u32 v79, v79, v172, s24
	v_and_or_b32 v77, v79, s22, v77
	global_store_dword v[206:207], v77, off offset:2304 nt
	v_mul_f32_e32 v77, v75, v198
	v_mul_f32_e32 v79, v75, v203
	v_bfe_u32 v172, v77, 16, 1
	v_add3_u32 v77, v77, v172, s24
	v_bfe_u32 v172, v79, 16, 1
	v_lshrrev_b32_e32 v77, 16, v77
	v_add3_u32 v79, v79, v172, s24
	v_and_or_b32 v77, v79, s22, v77
	global_store_dword v[206:207], v77, off offset:2560 nt
	v_mul_f32_e32 v77, v75, v199
	v_mul_f32_e32 v79, v75, v201
	v_bfe_u32 v172, v77, 16, 1
	v_add3_u32 v77, v77, v172, s24
	v_bfe_u32 v172, v79, 16, 1
	v_lshrrev_b32_e32 v77, 16, v77
	v_add3_u32 v79, v79, v172, s24
	v_and_or_b32 v77, v79, s22, v77
	global_store_dword v[206:207], v77, off offset:2816 nt
	v_mul_f32_e32 v77, v75, v195
	v_mul_f32_e32 v79, v75, v200
	v_bfe_u32 v172, v77, 16, 1
	v_add3_u32 v77, v77, v172, s24
	v_bfe_u32 v172, v79, 16, 1
	v_lshrrev_b32_e32 v77, 16, v77
	v_add3_u32 v79, v79, v172, s24
	v_and_or_b32 v77, v79, s22, v77
	global_store_dword v[206:207], v77, off offset:3072 nt
	v_mul_f32_e32 v77, v75, v193
	v_mul_f32_e32 v79, v75, v196
	v_bfe_u32 v172, v77, 16, 1
	v_add3_u32 v77, v77, v172, s24
	v_bfe_u32 v172, v79, 16, 1
	v_lshrrev_b32_e32 v77, 16, v77
	v_add3_u32 v79, v79, v172, s24
	v_and_or_b32 v77, v79, s22, v77
	global_store_dword v[206:207], v77, off offset:3328 nt
	v_mul_f32_e32 v77, v75, v192
	v_mul_f32_e32 v79, v75, v194
	v_bfe_u32 v172, v77, 16, 1
	v_add3_u32 v77, v77, v172, s24
	v_bfe_u32 v172, v79, 16, 1
	v_lshrrev_b32_e32 v77, 16, v77
	v_add3_u32 v79, v79, v172, s24
	v_and_or_b32 v77, v79, s22, v77
	global_store_dword v[206:207], v77, off offset:3584 nt
	v_fmamk_f32 v77, v81, 0x3a800000, v102
	v_mul_f32_e32 v79, 0x4f800000, v77
	v_cmp_gt_f32_e32 vcc, s23, v77
	v_mul_f32_e32 v192, 0x4f800000, v155
	v_mul_f32_e32 v81, v75, v191
	v_cndmask_b32_e32 v77, v77, v79, vcc
	v_sqrt_f32_e32 v79, v77
	v_mul_f32_e32 v75, v75, v204
	v_bfe_u32 v172, v81, 16, 1
	v_add3_u32 v81, v81, v172, s24
	v_add_u32_e32 v173, -1, v79
	v_fma_f32 v174, -v173, v79, v77
	v_cmp_ge_f32_e64 s[4:5], 0, v174
	v_add_u32_e32 v174, 1, v79
	v_bfe_u32 v172, v75, 16, 1
	v_cndmask_b32_e64 v173, v79, v173, s[4:5]
	v_fma_f32 v79, -v174, v79, v77
	v_cmp_lt_f32_e64 s[4:5], 0, v79
	v_lshrrev_b32_e32 v81, 16, v81
	v_add3_u32 v75, v75, v172, s24
	v_cndmask_b32_e64 v79, v173, v174, s[4:5]
	v_mul_f32_e32 v173, 0x37800000, v79
	v_cndmask_b32_e32 v79, v79, v173, vcc
	v_cmp_class_f32_e32 vcc, v77, v103
	v_cmp_gt_f32_e64 s[4:5], s23, v155
	v_and_or_b32 v75, v75, s22, v81
	v_cndmask_b32_e32 v77, v79, v77, vcc
	v_div_scale_f32 v79, s[0:1], v77, v77, 1.0
	v_rcp_f32_e32 v173, v79
	v_cndmask_b32_e64 v155, v155, v192, s[4:5]
	v_sqrt_f32_e32 v192, v155
	global_store_dword v[206:207], v75, off offset:3840 nt
	v_fma_f32 v174, -v79, v173, 1.0
	v_fmac_f32_e32 v173, v174, v173
	v_div_scale_f32 v174, vcc, 1.0, v77, 1.0
	v_mul_f32_e32 v191, v174, v173
	v_fma_f32 v193, -v79, v191, v174
	v_fmac_f32_e32 v191, v193, v173
	v_fma_f32 v79, -v79, v191, v174
	v_add_u32_e32 v174, -1, v192
	v_fma_f32 v193, -v174, v192, v155
	v_cmp_ge_f32_e64 s[6:7], 0, v193
	v_add_u32_e32 v193, 1, v192
	v_div_fmas_f32 v79, v79, v173, v191
	v_cndmask_b32_e64 v174, v192, v174, s[6:7]
	v_fma_f32 v192, -v193, v192, v155
	v_cmp_lt_f32_e64 s[6:7], 0, v192
	v_div_fixup_f32 v77, v79, v77, 1.0
	v_fmamk_f32 v27, v27, 0x3a800000, v102
	v_cndmask_b32_e64 v174, v174, v193, s[6:7]
	v_mul_f32_e32 v192, 0x37800000, v174
	v_cndmask_b32_e64 v174, v174, v192, s[4:5]
	v_cmp_class_f32_e64 s[4:5], v155, v103
	v_fmamk_f32 v107, v107, 0x3a800000, v102
	v_fmamk_f32 v23, v23, 0x3a800000, v102
	v_cndmask_b32_e64 v155, v174, v155, s[4:5]
	v_div_scale_f32 v174, s[0:1], v155, v155, 1.0
	v_rcp_f32_e32 v192, v174
	v_fmamk_f32 v106, v106, 0x3a800000, v102
	v_fmamk_f32 v19, v19, 0x3a800000, v102
	v_fmamk_f32 v15, v15, 0x3a800000, v102
	v_fma_f32 v79, -v174, v192, 1.0
	v_fmac_f32_e32 v192, v79, v192
	v_div_scale_f32 v79, vcc, 1.0, v155, 1.0
	v_mul_f32_e32 v173, v79, v192
	v_fma_f32 v191, -v174, v173, v79
	v_fmac_f32_e32 v173, v191, v192
	v_fma_f32 v79, -v174, v173, v79
	v_div_fmas_f32 v79, v79, v192, v173
	v_div_fixup_f32 v79, v79, v155, 1.0
	v_div_scale_f32 v155, s[0:1], v79, v79, v77
	v_rcp_f32_e32 v173, v155
	s_add_i32 s0, s12, 1
	s_ashr_i32 s1, s0, 31
	s_lshl_b64 s[0:1], s[0:1], 12
	v_fma_f32 v75, -v155, v173, 1.0
	v_fmac_f32_e32 v173, v75, v173
	v_div_scale_f32 v75, vcc, v77, v79, v77
	v_mul_f32_e32 v81, v75, v173
	v_fma_f32 v172, -v155, v81, v75
	v_fmac_f32_e32 v81, v172, v173
	v_fma_f32 v75, -v155, v81, v75
	v_div_fmas_f32 v75, v75, v173, v81
	v_div_fixup_f32 v75, v75, v79, v77
	v_mul_f32_e32 v77, v75, v189
	v_mul_f32_e32 v79, v75, v190
	v_bfe_u32 v81, v77, 16, 1
	v_add3_u32 v77, v77, v81, s24
	v_bfe_u32 v81, v79, 16, 1
	v_lshrrev_b32_e32 v77, 16, v77
	v_add3_u32 v79, v79, v81, s24
	v_lshl_add_u64 v[172:173], v[68:69], 0, s[0:1]
	v_and_or_b32 v77, v79, s22, v77
	global_store_dword v[172:173], v77, off offset:2048 nt
	v_mul_f32_e32 v77, v75, v187
	v_mul_f32_e32 v79, v75, v188
	v_bfe_u32 v81, v77, 16, 1
	v_add3_u32 v77, v77, v81, s24
	v_bfe_u32 v81, v79, 16, 1
	v_lshrrev_b32_e32 v77, 16, v77
	v_add3_u32 v79, v79, v81, s24
	v_and_or_b32 v77, v79, s22, v77
	global_store_dword v[172:173], v77, off offset:2304 nt
	v_mul_f32_e32 v77, v75, v185
	v_mul_f32_e32 v79, v75, v186
	v_bfe_u32 v81, v77, 16, 1
	v_add3_u32 v77, v77, v81, s24
	v_bfe_u32 v81, v79, 16, 1
	v_lshrrev_b32_e32 v77, 16, v77
	v_add3_u32 v79, v79, v81, s24
	v_and_or_b32 v77, v79, s22, v77
	global_store_dword v[172:173], v77, off offset:2560 nt
	v_mul_f32_e32 v77, v75, v183
	v_mul_f32_e32 v79, v75, v184
	v_bfe_u32 v81, v77, 16, 1
	v_add3_u32 v77, v77, v81, s24
	v_bfe_u32 v81, v79, 16, 1
	v_lshrrev_b32_e32 v77, 16, v77
	v_add3_u32 v79, v79, v81, s24
	v_and_or_b32 v77, v79, s22, v77
	global_store_dword v[172:173], v77, off offset:2816 nt
	v_mul_f32_e32 v77, v75, v181
	v_mul_f32_e32 v79, v75, v182
	v_bfe_u32 v81, v77, 16, 1
	v_add3_u32 v77, v77, v81, s24
	v_bfe_u32 v81, v79, 16, 1
	v_lshrrev_b32_e32 v77, 16, v77
	v_add3_u32 v79, v79, v81, s24
	v_and_or_b32 v77, v79, s22, v77
	global_store_dword v[172:173], v77, off offset:3072 nt
	v_mul_f32_e32 v77, v75, v179
	v_mul_f32_e32 v79, v75, v180
	v_bfe_u32 v81, v77, 16, 1
	v_add3_u32 v77, v77, v81, s24
	v_bfe_u32 v81, v79, 16, 1
	v_lshrrev_b32_e32 v77, 16, v77
	v_add3_u32 v79, v79, v81, s24
	v_and_or_b32 v77, v79, s22, v77
	global_store_dword v[172:173], v77, off offset:3328 nt
	v_mul_f32_e32 v77, v75, v177
	v_mul_f32_e32 v79, v75, v178
	v_bfe_u32 v81, v77, 16, 1
	v_add3_u32 v77, v77, v81, s24
	v_bfe_u32 v81, v79, 16, 1
	v_lshrrev_b32_e32 v77, 16, v77
	v_add3_u32 v79, v79, v81, s24
	v_and_or_b32 v77, v79, s22, v77
	global_store_dword v[172:173], v77, off offset:3584 nt
	v_fmamk_f32 v77, v205, 0x3a800000, v102
	v_mul_f32_e32 v79, 0x4f800000, v77
	v_cmp_gt_f32_e32 vcc, s23, v77
	v_mul_f32_e32 v81, v75, v175
	v_mul_f32_e32 v177, 0x4f800000, v122
	v_cndmask_b32_e32 v77, v77, v79, vcc
	v_sqrt_f32_e32 v79, v77
	v_mul_f32_e32 v75, v75, v176
	v_bfe_u32 v155, v81, 16, 1
	v_add3_u32 v81, v81, v155, s24
	v_add_u32_e32 v174, -1, v79
	v_fma_f32 v175, -v174, v79, v77
	v_cmp_ge_f32_e64 s[4:5], 0, v175
	v_add_u32_e32 v175, 1, v79
	v_bfe_u32 v155, v75, 16, 1
	v_cndmask_b32_e64 v174, v79, v174, s[4:5]
	v_fma_f32 v79, -v175, v79, v77
	v_cmp_lt_f32_e64 s[4:5], 0, v79
	v_lshrrev_b32_e32 v81, 16, v81
	v_add3_u32 v75, v75, v155, s24
	v_cndmask_b32_e64 v79, v174, v175, s[4:5]
	v_mul_f32_e32 v174, 0x37800000, v79
	v_cndmask_b32_e32 v79, v79, v174, vcc
	v_cmp_class_f32_e32 vcc, v77, v103
	v_cmp_gt_f32_e64 s[4:5], s23, v122
	v_and_or_b32 v75, v75, s22, v81
	v_cndmask_b32_e32 v77, v79, v77, vcc
	v_div_scale_f32 v79, s[0:1], v77, v77, 1.0
	v_rcp_f32_e32 v174, v79
	v_cndmask_b32_e64 v122, v122, v177, s[4:5]
	v_sqrt_f32_e32 v177, v122
	global_store_dword v[172:173], v75, off offset:3840 nt
	v_fma_f32 v175, -v79, v174, 1.0
	v_fmac_f32_e32 v174, v175, v174
	v_div_scale_f32 v175, vcc, 1.0, v77, 1.0
	v_mul_f32_e32 v176, v175, v174
	v_fma_f32 v178, -v79, v176, v175
	v_fmac_f32_e32 v176, v178, v174
	v_fma_f32 v79, -v79, v176, v175
	v_add_u32_e32 v175, -1, v177
	v_fma_f32 v178, -v175, v177, v122
	v_cmp_ge_f32_e64 s[6:7], 0, v178
	v_add_u32_e32 v178, 1, v177
	v_div_fmas_f32 v79, v79, v174, v176
	v_cndmask_b32_e64 v175, v177, v175, s[6:7]
	v_fma_f32 v177, -v178, v177, v122
	v_cmp_lt_f32_e64 s[6:7], 0, v177
	v_div_fixup_f32 v77, v79, v77, 1.0
	s_nop 0
	v_cndmask_b32_e64 v175, v175, v178, s[6:7]
	v_mul_f32_e32 v177, 0x37800000, v175
	v_cndmask_b32_e64 v175, v175, v177, s[4:5]
	v_cmp_class_f32_e64 s[4:5], v122, v103
	s_nop 1
	v_cndmask_b32_e64 v122, v175, v122, s[4:5]
	v_div_scale_f32 v175, s[0:1], v122, v122, 1.0
	v_rcp_f32_e32 v177, v175
	s_nop 0
	v_fma_f32 v79, -v175, v177, 1.0
	v_fmac_f32_e32 v177, v79, v177
	v_div_scale_f32 v79, vcc, 1.0, v122, 1.0
	v_mul_f32_e32 v174, v79, v177
	v_fma_f32 v176, -v175, v174, v79
	v_fmac_f32_e32 v174, v176, v177
	v_fma_f32 v79, -v175, v174, v79
	v_div_fmas_f32 v79, v79, v177, v174
	v_div_fixup_f32 v79, v79, v122, 1.0
	v_div_scale_f32 v122, s[0:1], v79, v79, v77
	v_rcp_f32_e32 v174, v122
	s_add_i32 s0, s12, 2
	s_ashr_i32 s1, s0, 31
	s_lshl_b64 s[0:1], s[0:1], 12
	v_fma_f32 v75, -v122, v174, 1.0
	v_fmac_f32_e32 v174, v75, v174
	v_div_scale_f32 v75, vcc, v77, v79, v77
	v_mul_f32_e32 v81, v75, v174
	v_fma_f32 v155, -v122, v81, v75
	v_fmac_f32_e32 v81, v155, v174
	v_fma_f32 v75, -v122, v81, v75
	v_div_fmas_f32 v75, v75, v174, v81
	v_div_fixup_f32 v75, v75, v79, v77
	v_mul_f32_e32 v77, v75, v170
	v_mul_f32_e32 v79, v75, v171
	v_bfe_u32 v81, v77, 16, 1
	v_add3_u32 v77, v77, v81, s24
	v_bfe_u32 v81, v79, 16, 1
	v_lshrrev_b32_e32 v77, 16, v77
	v_add3_u32 v79, v79, v81, s24
	v_lshl_add_u64 v[172:173], v[68:69], 0, s[0:1]
	v_and_or_b32 v77, v79, s22, v77
	global_store_dword v[172:173], v77, off offset:2048 nt
	v_mul_f32_e32 v77, v75, v168
	v_mul_f32_e32 v79, v75, v169
	v_bfe_u32 v81, v77, 16, 1
	v_add3_u32 v77, v77, v81, s24
	v_bfe_u32 v81, v79, 16, 1
	v_lshrrev_b32_e32 v77, 16, v77
	v_add3_u32 v79, v79, v81, s24
	v_and_or_b32 v77, v79, s22, v77
	global_store_dword v[172:173], v77, off offset:2304 nt
	v_mul_f32_e32 v77, v75, v166
	v_mul_f32_e32 v79, v75, v167
	v_bfe_u32 v81, v77, 16, 1
	v_add3_u32 v77, v77, v81, s24
	v_bfe_u32 v81, v79, 16, 1
	v_lshrrev_b32_e32 v77, 16, v77
	v_add3_u32 v79, v79, v81, s24
	v_and_or_b32 v77, v79, s22, v77
	global_store_dword v[172:173], v77, off offset:2560 nt
	v_mul_f32_e32 v77, v75, v164
	v_mul_f32_e32 v79, v75, v165
	v_bfe_u32 v81, v77, 16, 1
	v_add3_u32 v77, v77, v81, s24
	v_bfe_u32 v81, v79, 16, 1
	v_lshrrev_b32_e32 v77, 16, v77
	v_add3_u32 v79, v79, v81, s24
	v_and_or_b32 v77, v79, s22, v77
	global_store_dword v[172:173], v77, off offset:2816 nt
	v_mul_f32_e32 v77, v75, v162
	v_mul_f32_e32 v79, v75, v163
	v_bfe_u32 v81, v77, 16, 1
	v_add3_u32 v77, v77, v81, s24
	v_bfe_u32 v81, v79, 16, 1
	v_lshrrev_b32_e32 v77, 16, v77
	v_add3_u32 v79, v79, v81, s24
	v_and_or_b32 v77, v79, s22, v77
	global_store_dword v[172:173], v77, off offset:3072 nt
	v_mul_f32_e32 v77, v75, v160
	v_mul_f32_e32 v79, v75, v161
	v_bfe_u32 v81, v77, 16, 1
	v_add3_u32 v77, v77, v81, s24
	v_bfe_u32 v81, v79, 16, 1
	v_lshrrev_b32_e32 v77, 16, v77
	v_add3_u32 v79, v79, v81, s24
	v_and_or_b32 v77, v79, s22, v77
	global_store_dword v[172:173], v77, off offset:3328 nt
	v_mul_f32_e32 v77, v75, v158
	v_mul_f32_e32 v79, v75, v159
	v_bfe_u32 v81, v77, 16, 1
	v_add3_u32 v77, v77, v81, s24
	v_bfe_u32 v81, v79, 16, 1
	v_lshrrev_b32_e32 v77, 16, v77
	v_add3_u32 v79, v79, v81, s24
	v_and_or_b32 v77, v79, s22, v77
	global_store_dword v[172:173], v77, off offset:3584 nt
	v_mul_f32_e32 v77, 0x4f800000, v31
	v_cmp_gt_f32_e32 vcc, s23, v31
	v_mul_f32_e32 v79, v75, v156
	v_mul_f32_e32 v75, v75, v157
	v_cndmask_b32_e32 v31, v31, v77, vcc
	v_sqrt_f32_e32 v77, v31
	v_mul_f32_e32 v157, 0x4f800000, v108
	v_bfe_u32 v81, v79, 16, 1
	v_add3_u32 v79, v79, v81, s24
	v_add_u32_e32 v122, -1, v77
	v_fma_f32 v155, -v122, v77, v31
	v_cmp_ge_f32_e64 s[4:5], 0, v155
	v_add_u32_e32 v155, 1, v77
	v_bfe_u32 v81, v75, 16, 1
	v_cndmask_b32_e64 v122, v77, v122, s[4:5]
	v_fma_f32 v77, -v155, v77, v31
	v_cmp_lt_f32_e64 s[4:5], 0, v77
	v_lshrrev_b32_e32 v79, 16, v79
	v_add3_u32 v75, v75, v81, s24
	v_cndmask_b32_e64 v77, v122, v155, s[4:5]
	v_mul_f32_e32 v122, 0x37800000, v77
	v_cndmask_b32_e32 v77, v77, v122, vcc
	v_cmp_class_f32_e32 vcc, v31, v103
	v_cmp_gt_f32_e64 s[4:5], s23, v108
	v_and_or_b32 v75, v75, s22, v79
	v_cndmask_b32_e32 v31, v77, v31, vcc
	v_div_scale_f32 v77, s[0:1], v31, v31, 1.0
	v_rcp_f32_e32 v122, v77
	v_cndmask_b32_e64 v108, v108, v157, s[4:5]
	v_sqrt_f32_e32 v157, v108
	global_store_dword v[172:173], v75, off offset:3840 nt
	v_fma_f32 v155, -v77, v122, 1.0
	v_fmac_f32_e32 v122, v155, v122
	v_div_scale_f32 v155, vcc, 1.0, v31, 1.0
	v_mul_f32_e32 v156, v155, v122
	v_fma_f32 v158, -v77, v156, v155
	v_fmac_f32_e32 v156, v158, v122
	v_fma_f32 v77, -v77, v156, v155
	v_add_u32_e32 v155, -1, v157
	v_fma_f32 v158, -v155, v157, v108
	v_cmp_ge_f32_e64 s[6:7], 0, v158
	v_add_u32_e32 v158, 1, v157
	v_div_fmas_f32 v77, v77, v122, v156
	v_cndmask_b32_e64 v155, v157, v155, s[6:7]
	v_fma_f32 v157, -v158, v157, v108
	v_cmp_lt_f32_e64 s[6:7], 0, v157
	v_div_fixup_f32 v31, v77, v31, 1.0
	s_nop 0
	v_cndmask_b32_e64 v155, v155, v158, s[6:7]
	v_mul_f32_e32 v157, 0x37800000, v155
	v_cndmask_b32_e64 v155, v155, v157, s[4:5]
	v_cmp_class_f32_e64 s[4:5], v108, v103
	s_nop 1
	v_cndmask_b32_e64 v108, v155, v108, s[4:5]
	v_div_scale_f32 v155, s[0:1], v108, v108, 1.0
	v_rcp_f32_e32 v157, v155
	s_nop 0
	v_fma_f32 v77, -v155, v157, 1.0
	v_fmac_f32_e32 v157, v77, v157
	v_div_scale_f32 v77, vcc, 1.0, v108, 1.0
	v_mul_f32_e32 v122, v77, v157
	v_fma_f32 v156, -v155, v122, v77
	v_fmac_f32_e32 v122, v156, v157
	v_fma_f32 v77, -v155, v122, v77
	v_div_fmas_f32 v77, v77, v157, v122
	v_div_fixup_f32 v77, v77, v108, 1.0
	v_div_scale_f32 v108, s[0:1], v77, v77, v31
	v_rcp_f32_e32 v122, v108
	s_add_i32 s0, s12, 3
	s_ashr_i32 s1, s0, 31
	s_lshl_b64 s[0:1], s[0:1], 12
	v_fma_f32 v75, -v108, v122, 1.0
	v_fmac_f32_e32 v122, v75, v122
	v_div_scale_f32 v75, vcc, v31, v77, v31
	v_mul_f32_e32 v79, v75, v122
	v_fma_f32 v81, -v108, v79, v75
	v_fmac_f32_e32 v79, v81, v122
	v_fma_f32 v75, -v108, v79, v75
	v_div_fmas_f32 v75, v75, v122, v79
	v_div_fixup_f32 v31, v75, v77, v31
	v_mul_f32_e32 v75, v31, v153
	v_mul_f32_e32 v77, v31, v154
	v_bfe_u32 v79, v75, 16, 1
	v_add3_u32 v75, v75, v79, s24
	v_bfe_u32 v79, v77, 16, 1
	v_lshrrev_b32_e32 v75, 16, v75
	v_add3_u32 v77, v77, v79, s24
	v_lshl_add_u64 v[156:157], v[68:69], 0, s[0:1]
	v_and_or_b32 v75, v77, s22, v75
	global_store_dword v[156:157], v75, off offset:2048 nt
	v_mul_f32_e32 v75, v31, v151
	v_mul_f32_e32 v77, v31, v152
	v_bfe_u32 v79, v75, 16, 1
	v_add3_u32 v75, v75, v79, s24
	v_bfe_u32 v79, v77, 16, 1
	v_lshrrev_b32_e32 v75, 16, v75
	v_add3_u32 v77, v77, v79, s24
	v_and_or_b32 v75, v77, s22, v75
	global_store_dword v[156:157], v75, off offset:2304 nt
	v_mul_f32_e32 v75, v31, v149
	v_mul_f32_e32 v77, v31, v150
	v_bfe_u32 v79, v75, 16, 1
	v_add3_u32 v75, v75, v79, s24
	v_bfe_u32 v79, v77, 16, 1
	v_lshrrev_b32_e32 v75, 16, v75
	v_add3_u32 v77, v77, v79, s24
	v_and_or_b32 v75, v77, s22, v75
	global_store_dword v[156:157], v75, off offset:2560 nt
	v_mul_f32_e32 v75, v31, v147
	v_mul_f32_e32 v77, v31, v148
	v_bfe_u32 v79, v75, 16, 1
	v_add3_u32 v75, v75, v79, s24
	v_bfe_u32 v79, v77, 16, 1
	v_lshrrev_b32_e32 v75, 16, v75
	v_add3_u32 v77, v77, v79, s24
	v_and_or_b32 v75, v77, s22, v75
	global_store_dword v[156:157], v75, off offset:2816 nt
	v_mul_f32_e32 v75, v31, v145
	v_mul_f32_e32 v77, v31, v146
	v_bfe_u32 v79, v75, 16, 1
	v_add3_u32 v75, v75, v79, s24
	v_bfe_u32 v79, v77, 16, 1
	v_lshrrev_b32_e32 v75, 16, v75
	v_add3_u32 v77, v77, v79, s24
	v_and_or_b32 v75, v77, s22, v75
	global_store_dword v[156:157], v75, off offset:3072 nt
	v_mul_f32_e32 v75, v31, v143
	v_mul_f32_e32 v77, v31, v144
	v_bfe_u32 v79, v75, 16, 1
	v_add3_u32 v75, v75, v79, s24
	v_bfe_u32 v79, v77, 16, 1
	v_lshrrev_b32_e32 v75, 16, v75
	v_add3_u32 v77, v77, v79, s24
	v_and_or_b32 v75, v77, s22, v75
	global_store_dword v[156:157], v75, off offset:3328 nt
	v_mul_f32_e32 v75, v31, v141
	v_mul_f32_e32 v77, v31, v142
	v_bfe_u32 v79, v75, 16, 1
	v_add3_u32 v75, v75, v79, s24
	v_bfe_u32 v79, v77, 16, 1
	v_lshrrev_b32_e32 v75, 16, v75
	v_add3_u32 v77, v77, v79, s24
	v_and_or_b32 v75, v77, s22, v75
	global_store_dword v[156:157], v75, off offset:3584 nt
	v_mul_f32_e32 v75, 0x4f800000, v27
	v_cmp_gt_f32_e32 vcc, s23, v27
	v_mul_f32_e32 v77, v31, v139
	v_mul_f32_e32 v139, 0x4f800000, v107
	v_cndmask_b32_e32 v27, v27, v75, vcc
	v_sqrt_f32_e32 v75, v27
	v_mul_f32_e32 v31, v31, v140
	v_bfe_u32 v79, v77, 16, 1
	v_add3_u32 v77, v77, v79, s24
	v_add_u32_e32 v81, -1, v75
	v_fma_f32 v108, -v81, v75, v27
	v_cmp_ge_f32_e64 s[4:5], 0, v108
	v_add_u32_e32 v108, 1, v75
	v_bfe_u32 v79, v31, 16, 1
	v_cndmask_b32_e64 v81, v75, v81, s[4:5]
	v_fma_f32 v75, -v108, v75, v27
	v_cmp_lt_f32_e64 s[4:5], 0, v75
	v_lshrrev_b32_e32 v77, 16, v77
	v_add3_u32 v31, v31, v79, s24
	v_cndmask_b32_e64 v75, v81, v108, s[4:5]
	v_mul_f32_e32 v81, 0x37800000, v75
	v_cndmask_b32_e32 v75, v75, v81, vcc
	v_cmp_class_f32_e32 vcc, v27, v103
	v_cmp_gt_f32_e64 s[4:5], s23, v107
	v_and_or_b32 v31, v31, s22, v77
	v_cndmask_b32_e32 v27, v75, v27, vcc
	v_div_scale_f32 v75, s[0:1], v27, v27, 1.0
	v_rcp_f32_e32 v81, v75
	v_cndmask_b32_e64 v107, v107, v139, s[4:5]
	v_sqrt_f32_e32 v139, v107
	global_store_dword v[156:157], v31, off offset:3840 nt
	v_fma_f32 v108, -v75, v81, 1.0
	v_fmac_f32_e32 v81, v108, v81
	v_div_scale_f32 v108, vcc, 1.0, v27, 1.0
	v_mul_f32_e32 v122, v108, v81
	v_fma_f32 v140, -v75, v122, v108
	v_fmac_f32_e32 v122, v140, v81
	v_fma_f32 v75, -v75, v122, v108
	v_add_u32_e32 v108, -1, v139
	v_fma_f32 v140, -v108, v139, v107
	v_cmp_ge_f32_e64 s[6:7], 0, v140
	v_add_u32_e32 v140, 1, v139
	v_div_fmas_f32 v75, v75, v81, v122
	v_cndmask_b32_e64 v108, v139, v108, s[6:7]
	v_fma_f32 v139, -v140, v139, v107
	v_cmp_lt_f32_e64 s[6:7], 0, v139
	v_div_fixup_f32 v27, v75, v27, 1.0
	s_nop 0
	v_cndmask_b32_e64 v108, v108, v140, s[6:7]
	v_mul_f32_e32 v139, 0x37800000, v108
	v_cndmask_b32_e64 v108, v108, v139, s[4:5]
	v_cmp_class_f32_e64 s[4:5], v107, v103
	s_nop 1
	v_cndmask_b32_e64 v107, v108, v107, s[4:5]
	v_div_scale_f32 v108, s[0:1], v107, v107, 1.0
	v_rcp_f32_e32 v139, v108
	s_nop 0
	v_fma_f32 v75, -v108, v139, 1.0
	v_fmac_f32_e32 v139, v75, v139
	v_div_scale_f32 v75, vcc, 1.0, v107, 1.0
	v_mul_f32_e32 v81, v75, v139
	v_fma_f32 v122, -v108, v81, v75
	v_fmac_f32_e32 v81, v122, v139
	v_fma_f32 v75, -v108, v81, v75
	v_div_fmas_f32 v75, v75, v139, v81
	v_div_fixup_f32 v75, v75, v107, 1.0
	v_div_scale_f32 v81, s[0:1], v75, v75, v27
	v_rcp_f32_e32 v107, v81
	s_add_i32 s0, s12, 4
	s_ashr_i32 s1, s0, 31
	s_lshl_b64 s[0:1], s[0:1], 12
	v_fma_f32 v31, -v81, v107, 1.0
	v_fmac_f32_e32 v107, v31, v107
	v_div_scale_f32 v31, vcc, v27, v75, v27
	v_mul_f32_e32 v77, v31, v107
	v_fma_f32 v79, -v81, v77, v31
	v_fmac_f32_e32 v77, v79, v107
	v_fma_f32 v31, -v81, v77, v31
	v_div_fmas_f32 v31, v31, v107, v77
	v_div_fixup_f32 v27, v31, v75, v27
	v_mul_f32_e32 v31, v27, v132
	v_mul_f32_e32 v75, v27, v133
	v_bfe_u32 v77, v31, 16, 1
	v_add3_u32 v31, v31, v77, s24
	v_bfe_u32 v77, v75, 16, 1
	v_lshrrev_b32_e32 v31, 16, v31
	v_add3_u32 v75, v75, v77, s24
	v_lshl_add_u64 v[140:141], v[68:69], 0, s[0:1]
	v_and_or_b32 v31, v75, s22, v31
	global_store_dword v[140:141], v31, off offset:2048 nt
	v_mul_f32_e32 v31, v27, v130
	v_mul_f32_e32 v75, v27, v131
	v_bfe_u32 v77, v31, 16, 1
	v_add3_u32 v31, v31, v77, s24
	v_bfe_u32 v77, v75, 16, 1
	v_lshrrev_b32_e32 v31, 16, v31
	v_add3_u32 v75, v75, v77, s24
	v_and_or_b32 v31, v75, s22, v31
	global_store_dword v[140:141], v31, off offset:2304 nt
	v_mul_f32_e32 v31, v27, v128
	v_mul_f32_e32 v75, v27, v129
	v_bfe_u32 v77, v31, 16, 1
	v_add3_u32 v31, v31, v77, s24
	v_bfe_u32 v77, v75, 16, 1
	v_lshrrev_b32_e32 v31, 16, v31
	v_add3_u32 v75, v75, v77, s24
	v_and_or_b32 v31, v75, s22, v31
	global_store_dword v[140:141], v31, off offset:2560 nt
	v_mul_f32_e32 v31, v27, v126
	v_mul_f32_e32 v75, v27, v127
	v_bfe_u32 v77, v31, 16, 1
	v_add3_u32 v31, v31, v77, s24
	v_bfe_u32 v77, v75, 16, 1
	v_lshrrev_b32_e32 v31, 16, v31
	v_add3_u32 v75, v75, v77, s24
	v_and_or_b32 v31, v75, s22, v31
	global_store_dword v[140:141], v31, off offset:2816 nt
	v_mul_f32_e32 v31, v27, v123
	v_mul_f32_e32 v75, v27, v138
	v_bfe_u32 v77, v31, 16, 1
	v_add3_u32 v31, v31, v77, s24
	v_bfe_u32 v77, v75, 16, 1
	v_lshrrev_b32_e32 v31, 16, v31
	v_add3_u32 v75, v75, v77, s24
	v_and_or_b32 v31, v75, s22, v31
	global_store_dword v[140:141], v31, off offset:3072 nt
	v_mul_f32_e32 v31, v27, v136
	v_mul_f32_e32 v75, v27, v137
	v_bfe_u32 v77, v31, 16, 1
	v_add3_u32 v31, v31, v77, s24
	v_bfe_u32 v77, v75, 16, 1
	v_lshrrev_b32_e32 v31, 16, v31
	v_add3_u32 v75, v75, v77, s24
	v_and_or_b32 v31, v75, s22, v31
	global_store_dword v[140:141], v31, off offset:3328 nt
	v_mul_f32_e32 v31, v27, v134
	v_mul_f32_e32 v75, v27, v135
	v_bfe_u32 v77, v31, 16, 1
	v_add3_u32 v31, v31, v77, s24
	v_bfe_u32 v77, v75, 16, 1
	v_lshrrev_b32_e32 v31, 16, v31
	v_add3_u32 v75, v75, v77, s24
	v_and_or_b32 v31, v75, s22, v31
	global_store_dword v[140:141], v31, off offset:3584 nt
	v_mul_f32_e32 v31, 0x4f800000, v23
	v_cmp_gt_f32_e32 vcc, s23, v23
	v_mul_f32_e32 v108, 0x4f800000, v106
	v_mul_f32_e32 v75, v27, v124
	v_cndmask_b32_e32 v23, v23, v31, vcc
	v_sqrt_f32_e32 v31, v23
	v_mul_f32_e32 v27, v27, v125
	v_bfe_u32 v77, v75, 16, 1
	v_add3_u32 v75, v75, v77, s24
	v_add_u32_e32 v79, -1, v31
	v_fma_f32 v81, -v79, v31, v23
	v_cmp_ge_f32_e64 s[4:5], 0, v81
	v_add_u32_e32 v81, 1, v31
	v_bfe_u32 v77, v27, 16, 1
	v_cndmask_b32_e64 v79, v31, v79, s[4:5]
	v_fma_f32 v31, -v81, v31, v23
	v_cmp_lt_f32_e64 s[4:5], 0, v31
	v_lshrrev_b32_e32 v75, 16, v75
	v_add3_u32 v27, v27, v77, s24
	v_cndmask_b32_e64 v31, v79, v81, s[4:5]
	v_mul_f32_e32 v79, 0x37800000, v31
	v_cndmask_b32_e32 v31, v31, v79, vcc
	v_cmp_class_f32_e32 vcc, v23, v103
	v_cmp_gt_f32_e64 s[4:5], s23, v106
	v_and_or_b32 v27, v27, s22, v75
	v_cndmask_b32_e32 v23, v31, v23, vcc
	v_div_scale_f32 v31, s[0:1], v23, v23, 1.0
	v_rcp_f32_e32 v79, v31
	v_cndmask_b32_e64 v106, v106, v108, s[4:5]
	v_sqrt_f32_e32 v108, v106
	global_store_dword v[140:141], v27, off offset:3840 nt
	v_fma_f32 v81, -v31, v79, 1.0
	v_fmac_f32_e32 v79, v81, v79
	v_div_scale_f32 v81, vcc, 1.0, v23, 1.0
	v_mul_f32_e32 v107, v81, v79
	v_fma_f32 v122, -v31, v107, v81
	v_fmac_f32_e32 v107, v122, v79
	v_fma_f32 v31, -v31, v107, v81
	v_add_u32_e32 v81, -1, v108
	v_fma_f32 v122, -v81, v108, v106
	v_cmp_ge_f32_e64 s[6:7], 0, v122
	v_add_u32_e32 v122, 1, v108
	v_div_fmas_f32 v31, v31, v79, v107
	v_cndmask_b32_e64 v81, v108, v81, s[6:7]
	v_fma_f32 v108, -v122, v108, v106
	v_cmp_lt_f32_e64 s[6:7], 0, v108
	v_div_fixup_f32 v23, v31, v23, 1.0
	s_nop 0
	v_cndmask_b32_e64 v81, v81, v122, s[6:7]
	v_mul_f32_e32 v108, 0x37800000, v81
	v_cndmask_b32_e64 v81, v81, v108, s[4:5]
	v_cmp_class_f32_e64 s[4:5], v106, v103
	s_nop 1
	v_cndmask_b32_e64 v81, v81, v106, s[4:5]
	v_div_scale_f32 v106, s[0:1], v81, v81, 1.0
	v_rcp_f32_e32 v108, v106
	s_nop 0
	v_fma_f32 v31, -v106, v108, 1.0
	v_fmac_f32_e32 v108, v31, v108
	v_div_scale_f32 v31, vcc, 1.0, v81, 1.0
	v_mul_f32_e32 v79, v31, v108
	v_fma_f32 v107, -v106, v79, v31
	v_fmac_f32_e32 v79, v107, v108
	v_fma_f32 v31, -v106, v79, v31
	v_div_fmas_f32 v31, v31, v108, v79
	v_div_fixup_f32 v31, v31, v81, 1.0
	v_div_scale_f32 v79, s[0:1], v31, v31, v23
	v_rcp_f32_e32 v81, v79
	s_add_i32 s0, s12, 5
	s_ashr_i32 s1, s0, 31
	s_lshl_b64 s[0:1], s[0:1], 12
	v_fma_f32 v27, -v79, v81, 1.0
	v_fmac_f32_e32 v81, v27, v81
	v_div_scale_f32 v27, vcc, v23, v31, v23
	v_mul_f32_e32 v75, v27, v81
	v_fma_f32 v77, -v79, v75, v27
	v_fmac_f32_e32 v75, v77, v81
	v_fma_f32 v27, -v79, v75, v27
	v_div_fmas_f32 v27, v27, v81, v75
	v_div_fixup_f32 v23, v27, v31, v23
	v_mul_f32_e32 v27, v23, v120
	v_mul_f32_e32 v31, v23, v121
	v_bfe_u32 v75, v27, 16, 1
	v_add3_u32 v27, v27, v75, s24
	v_bfe_u32 v75, v31, 16, 1
	v_lshrrev_b32_e32 v27, 16, v27
	v_add3_u32 v31, v31, v75, s24
	v_lshl_add_u64 v[106:107], v[68:69], 0, s[0:1]
	v_and_or_b32 v27, v31, s22, v27
	global_store_dword v[106:107], v27, off offset:2048 nt
	v_mul_f32_e32 v27, v23, v118
	v_mul_f32_e32 v31, v23, v119
	v_bfe_u32 v75, v27, 16, 1
	v_add3_u32 v27, v27, v75, s24
	v_bfe_u32 v75, v31, 16, 1
	v_lshrrev_b32_e32 v27, 16, v27
	v_add3_u32 v31, v31, v75, s24
	v_and_or_b32 v27, v31, s22, v27
	global_store_dword v[106:107], v27, off offset:2304 nt
	v_mul_f32_e32 v27, v23, v116
	v_mul_f32_e32 v31, v23, v117
	v_bfe_u32 v75, v27, 16, 1
	v_add3_u32 v27, v27, v75, s24
	v_bfe_u32 v75, v31, 16, 1
	v_lshrrev_b32_e32 v27, 16, v27
	v_add3_u32 v31, v31, v75, s24
	v_and_or_b32 v27, v31, s22, v27
	global_store_dword v[106:107], v27, off offset:2560 nt
	v_mul_f32_e32 v27, v23, v114
	v_mul_f32_e32 v31, v23, v115
	v_bfe_u32 v75, v27, 16, 1
	v_add3_u32 v27, v27, v75, s24
	v_bfe_u32 v75, v31, 16, 1
	v_lshrrev_b32_e32 v27, 16, v27
	v_add3_u32 v31, v31, v75, s24
	v_and_or_b32 v27, v31, s22, v27
	global_store_dword v[106:107], v27, off offset:2816 nt
	v_mul_f32_e32 v27, v23, v112
	v_mul_f32_e32 v31, v23, v113
	v_bfe_u32 v75, v27, 16, 1
	v_add3_u32 v27, v27, v75, s24
	v_bfe_u32 v75, v31, 16, 1
	v_lshrrev_b32_e32 v27, 16, v27
	v_add3_u32 v31, v31, v75, s24
	v_and_or_b32 v27, v31, s22, v27
	global_store_dword v[106:107], v27, off offset:3072 nt
	v_mul_f32_e32 v27, v23, v110
	v_mul_f32_e32 v31, v23, v111
	v_bfe_u32 v75, v27, 16, 1
	v_add3_u32 v27, v27, v75, s24
	v_bfe_u32 v75, v31, 16, 1
	v_lshrrev_b32_e32 v27, 16, v27
	v_add3_u32 v31, v31, v75, s24
	v_and_or_b32 v27, v31, s22, v27
	global_store_dword v[106:107], v27, off offset:3328 nt
	v_mul_f32_e32 v27, v23, v80
	v_mul_f32_e32 v31, v23, v109
	v_bfe_u32 v75, v27, 16, 1
	v_add3_u32 v27, v27, v75, s24
	v_bfe_u32 v75, v31, 16, 1
	v_lshrrev_b32_e32 v27, 16, v27
	v_add3_u32 v31, v31, v75, s24
	v_and_or_b32 v27, v31, s22, v27
	global_store_dword v[106:107], v27, off offset:3584 nt
	v_mul_f32_e32 v27, 0x4f800000, v19
	v_cmp_gt_f32_e32 vcc, s23, v19
	v_mul_f32_e32 v31, v23, v76
	v_fmamk_f32 v79, v105, 0x3a800000, v102
	v_cndmask_b32_e32 v19, v19, v27, vcc
	v_sqrt_f32_e32 v27, v19
	v_mul_f32_e32 v80, 0x4f800000, v79
	v_mul_f32_e32 v23, v23, v78
	v_bfe_u32 v75, v31, 16, 1
	v_add_u32_e32 v76, -1, v27
	v_fma_f32 v77, -v76, v27, v19
	v_cmp_ge_f32_e64 s[4:5], 0, v77
	v_add_u32_e32 v77, 1, v27
	v_add3_u32 v31, v31, v75, s24
	v_cndmask_b32_e64 v76, v27, v76, s[4:5]
	v_fma_f32 v27, -v77, v27, v19
	v_cmp_lt_f32_e64 s[4:5], 0, v27
	v_bfe_u32 v75, v23, 16, 1
	v_lshrrev_b32_e32 v31, 16, v31
	v_cndmask_b32_e64 v27, v76, v77, s[4:5]
	v_mul_f32_e32 v76, 0x37800000, v27
	v_cndmask_b32_e32 v27, v27, v76, vcc
	v_cmp_class_f32_e32 vcc, v19, v103
	v_cmp_gt_f32_e64 s[4:5], s23, v79
	v_add3_u32 v23, v23, v75, s24
	v_cndmask_b32_e32 v19, v27, v19, vcc
	v_div_scale_f32 v27, s[0:1], v19, v19, 1.0
	v_rcp_f32_e32 v76, v27
	v_cndmask_b32_e64 v79, v79, v80, s[4:5]
	v_sqrt_f32_e32 v80, v79
	v_and_or_b32 v23, v23, s22, v31
	v_fma_f32 v77, -v27, v76, 1.0
	v_fmac_f32_e32 v76, v77, v76
	v_div_scale_f32 v77, vcc, 1.0, v19, 1.0
	v_mul_f32_e32 v78, v77, v76
	v_fma_f32 v81, -v27, v78, v77
	v_fmac_f32_e32 v78, v81, v76
	v_fma_f32 v27, -v27, v78, v77
	v_add_u32_e32 v77, -1, v80
	v_fma_f32 v81, -v77, v80, v79
	v_cmp_ge_f32_e64 s[6:7], 0, v81
	v_add_u32_e32 v81, 1, v80
	v_div_fmas_f32 v27, v27, v76, v78
	v_cndmask_b32_e64 v77, v80, v77, s[6:7]
	v_fma_f32 v80, -v81, v80, v79
	v_cmp_lt_f32_e64 s[6:7], 0, v80
	v_div_fixup_f32 v19, v27, v19, 1.0
	global_store_dword v[106:107], v23, off offset:3840 nt
	v_cndmask_b32_e64 v77, v77, v81, s[6:7]
	v_mul_f32_e32 v80, 0x37800000, v77
	v_cndmask_b32_e64 v77, v77, v80, s[4:5]
	v_cmp_class_f32_e64 s[4:5], v79, v103
	s_nop 1
	v_cndmask_b32_e64 v77, v77, v79, s[4:5]
	v_div_scale_f32 v79, s[0:1], v77, v77, 1.0
	v_rcp_f32_e32 v80, v79
	s_nop 0
	v_fma_f32 v27, -v79, v80, 1.0
	v_fmac_f32_e32 v80, v27, v80
	v_div_scale_f32 v27, vcc, 1.0, v77, 1.0
	v_mul_f32_e32 v76, v27, v80
	v_fma_f32 v78, -v79, v76, v27
	v_fmac_f32_e32 v76, v78, v80
	v_fma_f32 v27, -v79, v76, v27
	v_div_fmas_f32 v27, v27, v80, v76
	v_div_fixup_f32 v27, v27, v77, 1.0
	v_div_scale_f32 v76, s[0:1], v27, v27, v19
	v_rcp_f32_e32 v77, v76
	s_add_i32 s0, s12, 6
	s_ashr_i32 s1, s0, 31
	s_lshl_b64 s[0:1], s[0:1], 12
	v_fma_f32 v23, -v76, v77, 1.0
	v_fmac_f32_e32 v77, v23, v77
	v_div_scale_f32 v23, vcc, v19, v27, v19
	v_mul_f32_e32 v31, v23, v77
	v_fma_f32 v75, -v76, v31, v23
	v_fmac_f32_e32 v31, v75, v77
	v_fma_f32 v23, -v76, v31, v23
	v_div_fmas_f32 v23, v23, v77, v31
	v_div_fixup_f32 v19, v23, v27, v19
	v_mul_f32_e32 v23, v19, v73
	v_mul_f32_e32 v27, v19, v74
	v_bfe_u32 v31, v23, 16, 1
	v_add3_u32 v23, v23, v31, s24
	v_bfe_u32 v31, v27, 16, 1
	v_lshrrev_b32_e32 v23, 16, v23
	v_add3_u32 v27, v27, v31, s24
	v_lshl_add_u64 v[76:77], v[68:69], 0, s[0:1]
	v_and_or_b32 v23, v27, s22, v23
	global_store_dword v[76:77], v23, off offset:2048 nt
	v_mul_f32_e32 v23, v19, v71
	v_mul_f32_e32 v27, v19, v72
	v_bfe_u32 v31, v23, 16, 1
	v_add3_u32 v23, v23, v31, s24
	v_bfe_u32 v31, v27, 16, 1
	v_lshrrev_b32_e32 v23, 16, v23
	v_add3_u32 v27, v27, v31, s24
	v_and_or_b32 v23, v27, s22, v23
	global_store_dword v[76:77], v23, off offset:2304 nt
	v_mul_f32_e32 v23, v19, v30
	v_mul_f32_e32 v27, v19, v70
	v_bfe_u32 v30, v23, 16, 1
	v_add3_u32 v23, v23, v30, s24
	v_bfe_u32 v30, v27, 16, 1
	v_lshrrev_b32_e32 v23, 16, v23
	v_add3_u32 v27, v27, v30, s24
	v_and_or_b32 v23, v27, s22, v23
	global_store_dword v[76:77], v23, off offset:2560 nt
	v_mul_f32_e32 v23, v19, v28
	v_mul_f32_e32 v27, v19, v29
	v_bfe_u32 v28, v23, 16, 1
	v_add3_u32 v23, v23, v28, s24
	v_bfe_u32 v28, v27, 16, 1
	v_lshrrev_b32_e32 v23, 16, v23
	v_add3_u32 v27, v27, v28, s24
	v_and_or_b32 v23, v27, s22, v23
	global_store_dword v[76:77], v23, off offset:2816 nt
	v_mul_f32_e32 v23, v19, v25
	v_mul_f32_e32 v25, v19, v26
	v_bfe_u32 v26, v23, 16, 1
	v_add3_u32 v23, v23, v26, s24
	v_bfe_u32 v26, v25, 16, 1
	v_lshrrev_b32_e32 v23, 16, v23
	v_add3_u32 v25, v25, v26, s24
	v_and_or_b32 v23, v25, s22, v23
	v_mul_f32_e32 v22, v19, v22
	global_store_dword v[76:77], v23, off offset:3072 nt
	v_mul_f32_e32 v23, v19, v24
	v_bfe_u32 v24, v22, 16, 1
	v_add3_u32 v22, v22, v24, s24
	v_bfe_u32 v24, v23, 16, 1
	v_lshrrev_b32_e32 v22, 16, v22
	v_add3_u32 v23, v23, v24, s24
	v_and_or_b32 v22, v23, s22, v22
	v_mul_f32_e32 v20, v19, v20
	global_store_dword v[76:77], v22, off offset:3328 nt
	v_mul_f32_e32 v21, v19, v21
	v_bfe_u32 v22, v20, 16, 1
	v_add3_u32 v20, v20, v22, s24
	v_bfe_u32 v22, v21, 16, 1
	v_lshrrev_b32_e32 v20, 16, v20
	v_add3_u32 v21, v21, v22, s24
	v_and_or_b32 v20, v21, s22, v20
	global_store_dword v[76:77], v20, off offset:3584 nt
	v_mul_f32_e32 v20, 0x4f800000, v15
	v_cmp_gt_f32_e32 vcc, s23, v15
	v_fmamk_f32 v24, v104, 0x3a800000, v102
	v_mul_f32_e32 v25, 0x4f800000, v24
	v_cndmask_b32_e32 v15, v15, v20, vcc
	v_sqrt_f32_e32 v20, v15
	v_mul_f32_e32 v17, v19, v17
	v_mul_f32_e32 v18, v19, v18
	v_bfe_u32 v19, v17, 16, 1
	v_add_u32_e32 v21, -1, v20
	v_fma_f32 v22, -v21, v20, v15
	v_cmp_ge_f32_e64 s[4:5], 0, v22
	v_add_u32_e32 v22, 1, v20
	v_add3_u32 v17, v17, v19, s24
	v_cndmask_b32_e64 v21, v20, v21, s[4:5]
	v_fma_f32 v20, -v22, v20, v15
	v_cmp_lt_f32_e64 s[4:5], 0, v20
	v_bfe_u32 v19, v18, 16, 1
	v_lshrrev_b32_e32 v17, 16, v17
	v_cndmask_b32_e64 v20, v21, v22, s[4:5]
	v_mul_f32_e32 v21, 0x37800000, v20
	v_cndmask_b32_e32 v20, v20, v21, vcc
	v_cmp_class_f32_e32 vcc, v15, v103
	v_cmp_gt_f32_e64 s[4:5], s23, v24
	v_add3_u32 v18, v18, v19, s24
	v_cndmask_b32_e32 v15, v20, v15, vcc
	v_div_scale_f32 v20, s[0:1], v15, v15, 1.0
	v_rcp_f32_e32 v21, v20
	v_cndmask_b32_e64 v24, v24, v25, s[4:5]
	v_sqrt_f32_e32 v25, v24
	v_and_or_b32 v17, v18, s22, v17
	v_fma_f32 v22, -v20, v21, 1.0
	v_fmac_f32_e32 v21, v22, v21
	v_div_scale_f32 v22, vcc, 1.0, v15, 1.0
	v_mul_f32_e32 v23, v22, v21
	v_fma_f32 v26, -v20, v23, v22
	v_fmac_f32_e32 v23, v26, v21
	v_fma_f32 v20, -v20, v23, v22
	v_add_u32_e32 v22, -1, v25
	v_fma_f32 v26, -v22, v25, v24
	v_cmp_ge_f32_e64 s[6:7], 0, v26
	v_add_u32_e32 v26, 1, v25
	v_div_fmas_f32 v20, v20, v21, v23
	v_cndmask_b32_e64 v22, v25, v22, s[6:7]
	v_fma_f32 v25, -v26, v25, v24
	v_cmp_lt_f32_e64 s[6:7], 0, v25
	v_div_fixup_f32 v15, v20, v15, 1.0
	global_store_dword v[76:77], v17, off offset:3840 nt
	v_cndmask_b32_e64 v22, v22, v26, s[6:7]
	v_mul_f32_e32 v25, 0x37800000, v22
	v_cndmask_b32_e64 v22, v22, v25, s[4:5]
	v_cmp_class_f32_e64 s[4:5], v24, v103
	s_nop 1
	v_cndmask_b32_e64 v22, v22, v24, s[4:5]
	v_div_scale_f32 v24, s[0:1], v22, v22, 1.0
	v_rcp_f32_e32 v25, v24
	s_nop 0
	v_fma_f32 v20, -v24, v25, 1.0
	v_fmac_f32_e32 v25, v20, v25
	v_div_scale_f32 v20, vcc, 1.0, v22, 1.0
	v_mul_f32_e32 v21, v20, v25
	v_fma_f32 v23, -v24, v21, v20
	v_fmac_f32_e32 v21, v23, v25
	v_fma_f32 v20, -v24, v21, v20
	v_div_fmas_f32 v20, v20, v25, v21
	v_div_fixup_f32 v20, v20, v22, 1.0
	v_div_scale_f32 v21, s[0:1], v20, v20, v15
	v_rcp_f32_e32 v22, v21
	s_add_i32 s0, s12, 7
	s_ashr_i32 s1, s0, 31
	s_lshl_b64 s[0:1], s[0:1], 12
	v_fma_f32 v17, -v21, v22, 1.0
	v_fmac_f32_e32 v22, v17, v22
	v_div_scale_f32 v17, vcc, v15, v20, v15
	v_mul_f32_e32 v18, v17, v22
	v_fma_f32 v19, -v21, v18, v17
	v_fmac_f32_e32 v18, v19, v22
	v_fma_f32 v17, -v21, v18, v17
	v_div_fmas_f32 v17, v17, v22, v18
	v_div_fixup_f32 v15, v17, v20, v15
	v_mul_f32_e32 v14, v15, v14
	v_mul_f32_e32 v16, v15, v16
	v_bfe_u32 v17, v14, 16, 1
	v_add3_u32 v14, v14, v17, s24
	v_bfe_u32 v17, v16, 16, 1
	v_lshrrev_b32_e32 v14, 16, v14
	v_add3_u32 v16, v16, v17, s24
	v_lshl_add_u64 v[18:19], v[68:69], 0, s[0:1]
	v_and_or_b32 v14, v16, s22, v14
	v_mul_f32_e32 v12, v15, v12
	global_store_dword v[18:19], v14, off offset:2048 nt
	v_mul_f32_e32 v13, v15, v13
	v_bfe_u32 v14, v12, 16, 1
	v_add3_u32 v12, v12, v14, s24
	v_bfe_u32 v14, v13, 16, 1
	v_lshrrev_b32_e32 v12, 16, v12
	v_add3_u32 v13, v13, v14, s24
	v_and_or_b32 v12, v13, s22, v12
	v_mul_f32_e32 v10, v15, v10
	global_store_dword v[18:19], v12, off offset:2304 nt
	v_mul_f32_e32 v11, v15, v11
	v_bfe_u32 v12, v10, 16, 1
	v_add3_u32 v10, v10, v12, s24
	v_bfe_u32 v12, v11, 16, 1
	v_lshrrev_b32_e32 v10, 16, v10
	v_add3_u32 v11, v11, v12, s24
	v_and_or_b32 v10, v11, s22, v10
	v_mul_f32_e32 v8, v15, v8
	global_store_dword v[18:19], v10, off offset:2560 nt
	v_mul_f32_e32 v9, v15, v9
	v_bfe_u32 v10, v8, 16, 1
	v_add3_u32 v8, v8, v10, s24
	v_bfe_u32 v10, v9, 16, 1
	v_lshrrev_b32_e32 v8, 16, v8
	v_add3_u32 v9, v9, v10, s24
	v_and_or_b32 v8, v9, s22, v8
	v_mul_f32_e32 v6, v15, v6
	global_store_dword v[18:19], v8, off offset:2816 nt
	v_mul_f32_e32 v7, v15, v7
	v_bfe_u32 v8, v6, 16, 1
	v_add3_u32 v6, v6, v8, s24
	v_bfe_u32 v8, v7, 16, 1
	v_lshrrev_b32_e32 v6, 16, v6
	v_add3_u32 v7, v7, v8, s24
	v_and_or_b32 v6, v7, s22, v6
	v_mul_f32_e32 v4, v15, v4
	global_store_dword v[18:19], v6, off offset:3072 nt
	v_mul_f32_e32 v5, v15, v5
	v_bfe_u32 v6, v4, 16, 1
	v_add3_u32 v4, v4, v6, s24
	v_bfe_u32 v6, v5, 16, 1
	v_lshrrev_b32_e32 v4, 16, v4
	v_add3_u32 v5, v5, v6, s24
	v_and_or_b32 v4, v5, s22, v4
	v_mul_f32_e32 v2, v15, v2
	global_store_dword v[18:19], v4, off offset:3328 nt
	v_mul_f32_e32 v3, v15, v3
	v_bfe_u32 v4, v2, 16, 1
	v_add3_u32 v2, v2, v4, s24
	v_bfe_u32 v4, v3, 16, 1
	v_lshrrev_b32_e32 v2, 16, v2
	v_add3_u32 v3, v3, v4, s24
	v_and_or_b32 v2, v3, s22, v2
	v_mul_f32_e32 v0, v15, v0
	global_store_dword v[18:19], v2, off offset:3584 nt
	v_mul_f32_e32 v1, v15, v1
	v_bfe_u32 v2, v0, 16, 1
	v_add3_u32 v0, v0, v2, s24
	v_bfe_u32 v2, v1, 16, 1
	v_lshrrev_b32_e32 v0, 16, v0
	v_add3_u32 v1, v1, v2, s24
	v_and_or_b32 v0, v1, s22, v0
	s_cmpk_lt_i32 s15, 0x100
	global_store_dword v[18:19], v0, off offset:3840 nt
	s_waitcnt vmcnt(63) expcnt(7) lgkmcnt(15)
	s_barrier
	s_cbranch_scc1 .LBB0_474
